# v84 + prep_run row loop: store-drain waits removed (loop-top vmcnt0 moved to preamble, latch vmcnt2 removed, window path gets explicit vmcnt0)
# speedup vs baseline: 1.0029x; 1.0029x over previous
.LBB0_447:
	s_and_b64 vcc, exec, s[0:1]
	s_cbranch_vccz .LBB0_557
	s_movk_i32 s0, 0xff
	v_cmp_lt_i32_e32 vcc, s0, v81
	s_and_saveexec_b64 s[0:1], vcc
	s_xor_b64 s[42:43], exec, s[0:1]
	s_cbranch_execz .LBB0_531
	s_movk_i32 s0, 0x33f
	v_cmp_lt_u32_e32 vcc, s0, v81
	s_and_saveexec_b64 s[0:1], vcc
	s_xor_b64 s[16:17], exec, s[0:1]
	s_cbranch_execz .LBB0_501
	s_movk_i32 s0, 0x4bf
	v_cmp_lt_u32_e32 vcc, s0, v81
	v_readlane_b32 s4, v254, 28
	v_readlane_b32 s0, v255, 7
	v_readlane_b32 s5, v254, 29
	s_add_u32 s2, s4, 0x16f00000
	v_readlane_b32 s1, v255, 8
	s_addc_u32 s3, s5, 0
	s_lshl_b64 s[0:1], s[0:1], 2
	s_add_u32 s0, s4, s0
	s_addc_u32 s1, s5, s1
	s_add_u32 s18, s0, 0x2000
	s_addc_u32 s19, s1, 0
	s_and_saveexec_b64 s[0:1], vcc
	s_xor_b64 s[28:29], exec, s[0:1]
	s_cbranch_execz .LBB0_475
	v_mov_b32_e32 v0, 0xfffff800
	v_mov_b32_e32 v1, -1
	v_mad_u64_u32 v[8:9], s[0:1], v81, 10, v[0:1]
	v_mov_b32_e32 v9, v236
	v_readlane_b32 s4, v255, 11
	v_and_b32_e32 v17, 15, v9
	v_bfe_u32 v19, v9, 4, 2
	v_lshlrev_b32_e32 v21, 2, v17
	v_lshlrev_b32_e32 v12, 6, v19
	v_or_b32_e32 v23, 8, v19
	v_readlane_b32 s5, v255, 12
	v_or_b32_e32 v20, 0x100, v21
	v_min_u32_e32 v0, 9, v23
	v_mov_b64_e32 v[10:11], s[4:5]
	s_movk_i32 s0, 0x1200
	v_or_b32_e32 v22, v12, v21
	v_or_b32_e32 v16, v12, v20
	v_lshlrev_b32_e32 v25, 6, v0
	v_mad_i64_i32 v[10:11], s[0:1], v8, s0, v[10:11]
	v_lshlrev_b32_e32 v160, 1, v22
	v_lshl_add_u64 v[12:13], v[10:11], 0, v[160:161]
	v_lshlrev_b32_e32 v160, 1, v16
	v_or_b32_e32 v24, v25, v21
	v_lshlrev_b32_e32 v4, 4, v17
	v_lshl_add_u64 v[14:15], v[10:11], 0, v[160:161]
	v_lshlrev_b32_e32 v160, 1, v24
	global_load_dwordx4 v[0:3], v4, s[18:19]
	s_nop 0
	global_load_dwordx4 v[4:7], v4, s[18:19] offset:1024
	v_lshl_add_u64 v[10:11], v[10:11], 0, v[160:161]
	global_load_dwordx2 v[46:47], v[12:13], off offset:512
	global_load_dwordx2 v[44:45], v[14:15], off offset:512
	global_load_dwordx2 v[38:39], v[10:11], off offset:512
	v_and_b32_e32 v10, 63, v9
	v_and_b32_e32 v9, 4, v9
	v_cmp_eq_u32_e64 s[36:37], 0, v9
	v_and_b32_e32 v9, 12, v21
	v_cvt_f32_ubyte0_e32 v14, v9
	v_mul_f32_e32 v14, 0xbf549a78, v14
	v_exp_f32_e32 v59, v14
	v_or_b32_e32 v14, 1, v9
	v_cvt_f32_ubyte0_e32 v14, v14
	v_mul_f32_e32 v14, 0xbf549a78, v14
	v_exp_f32_e32 v60, v14
	v_or_b32_e32 v14, 2, v9
	v_or_b32_e32 v9, 3, v9
	v_cvt_f32_ubyte0_e32 v14, v14
	v_cvt_f32_ubyte0_e32 v9, v9
	v_mul_f32_e32 v14, 0xbf549a78, v14
	v_mul_f32_e32 v9, 0xbf549a78, v9
	v_exp_f32_e32 v61, v14
	v_exp_f32_e32 v62, v9
	v_readlane_b32 s0, v254, 28
	v_add_u32_e32 v18, 0x100, v16
	v_or_b32_e32 v20, v25, v20
	v_mov_b32_e32 v64, 0
	v_lshlrev_b32_e32 v160, 3, v10
	v_readlane_b32 s1, v254, 29
	v_cmp_gt_u32_e32 vcc, 10, v23
	v_lshlrev_b32_e64 v58, v19, 1
	v_lshl_add_u64 v[10:11], s[4:5], 0, v[160:161]
	v_cmp_gt_u32_e64 s[38:39], 8, v17
	v_lshl_add_u64 v[12:13], s[2:3], 0, v[160:161]
	v_lshl_add_u64 v[14:15], s[0:1], 0, v[160:161]
	s_mov_b32 s14, 0
	v_lshlrev_b32_e32 v16, 1, v16
	v_lshlrev_b32_e32 v18, 1, v18
	v_lshlrev_b32_e32 v20, 1, v20
	v_lshlrev_b32_e32 v22, 1, v22
	v_lshlrev_b32_e32 v24, 1, v24
	v_mov_b32_e32 v63, v8
	v_mov_b32_e32 v23, 0
	v_mov_b32_e32 v40, 0
	v_mov_b32_e32 v41, v64
	v_mov_b32_e32 v42, 0
	v_mov_b32_e32 v43, v64
	s_waitcnt vmcnt(0)
	s_branch .LBB0_453
.LBB0_452:
	s_or_b64 exec, exec, s[0:1]
	v_sub_u32_e32 v9, v19, v64
	v_cvt_f32_i32_e32 v9, v9
	v_lshlrev_b32_e32 v38, 16, v36
	v_and_b32_e32 v39, 0xffff0000, v36
	s_add_i32 s14, s14, 1
	v_rcp_iflag_f32_e32 v34, v9
	v_lshlrev_b64 v[26:27], 11, v[26:27]
	v_lshl_add_u64 v[26:27], v[12:13], 0, v[26:27]
	v_add_u32_e32 v63, 1, v63
	v_pk_fma_f32 v[38:39], v[34:35], v[42:43], v[38:39] op_sel_hi:[0,1,1] neg_lo:[0,0,1] neg_hi:[0,0,1]
	v_cvt_pk_bf16_f32 v36, v38, v39
	v_lshlrev_b32_e32 v38, 16, v37
	v_and_b32_e32 v39, 0xffff0000, v37
	v_pk_fma_f32 v[34:35], v[34:35], v[40:41], v[38:39] op_sel_hi:[0,1,1] neg_lo:[0,0,1] neg_hi:[0,0,1]
	v_cvt_pk_bf16_f32 v37, v34, v35
	s_cmp_eq_u32 s14, 10
	v_mov_b32_e32 v23, v19
	v_mov_b32_e32 v46, v28
	v_mov_b32_e32 v47, v29
	v_mov_b32_e32 v44, v30
	v_mov_b32_e32 v45, v31
	v_mov_b32_e32 v38, v32
	v_mov_b32_e32 v39, v33
	global_store_dwordx2 v[26:27], v[36:37], off
	s_cbranch_scc1 .LBB0_475
.LBB0_453:
	v_readlane_b32 s0, v255, 11
	v_readlane_b32 s1, v255, 12
	v_add_u32_e32 v26, s14, v8
	s_cmp_gt_u32 s14, 8
	v_mov_b64_e32 v[28:29], s[0:1]
	s_movk_i32 s0, 0x1200
	v_mad_i64_i32 v[34:35], s[0:1], v26, s0, v[28:29]
	v_mov_b32_e32 v28, v46
	v_mov_b32_e32 v29, v47
	v_mov_b32_e32 v30, v44
	v_mov_b32_e32 v31, v45
	v_mov_b32_e32 v32, v38
	v_mov_b32_e32 v33, v39
	s_cbranch_scc1 .LBB0_455
	v_lshl_add_u64 v[28:29], v[34:35], 0, s[34:35]
	v_mov_b32_e32 v17, v161
	v_mov_b32_e32 v19, v161
	v_lshl_add_u64 v[30:31], v[28:29], 0, v[16:17]
	v_lshl_add_u64 v[32:33], v[28:29], 0, v[18:19]
	v_mov_b32_e32 v21, v161
	v_lshl_add_u64 v[36:37], v[28:29], 0, v[20:21]
	global_load_dwordx2 v[28:29], v[30:31], off
	s_nop 0
	global_load_dwordx2 v[30:31], v[32:33], off
	s_nop 0
	global_load_dwordx2 v[32:33], v[36:37], off

.LBB0_471:
	s_or_b64 exec, exec, s[8:9]
.LBB0_472:
	s_or_b64 exec, exec, s[6:7]
	s_waitcnt vmcnt(0)
.LBB0_473:
	s_or_b64 exec, exec, s[4:5]
	v_lshrrev_b32_e32 v9, 6, v9
	v_and_b32_e32 v17, 63, v26
	v_cndmask_b32_e64 v9, v17, v9, s[38:39]
	v_cvt_f32_ubyte0_e32 v9, v9
	v_mul_f32_e32 v17, v59, v9
	v_mul_f32_e32 v17, 0.15915494, v17
	v_cos_f32_e32 v51, v17
	v_sin_f32_e32 v56, v17
	v_mul_f32_e32 v17, v60, v9
	v_mul_f32_e32 v17, 0.15915494, v17
	v_cos_f32_e32 v49, v17
	v_sin_f32_e32 v50, v17
	v_mul_f32_e32 v17, v61, v9
	v_lshlrev_b32_e32 v53, 16, v47
	v_lshlrev_b32_e32 v52, 16, v46
	v_and_b32_e32 v47, 0xffff0000, v47
	v_and_b32_e32 v46, 0xffff0000, v46
	v_mul_f32_e32 v17, 0.15915494, v17
	v_mul_f32_e32 v9, v62, v9
	v_pk_mul_f32 v[54:55], v[46:47], v[46:47]
	v_cos_f32_e32 v25, v17
	v_sin_f32_e32 v48, v17
	v_mul_f32_e32 v17, 0.15915494, v9
	v_pk_fma_f32 v[54:55], v[52:53], v[52:53], v[54:55]
	v_cos_f32_e32 v9, v17
	v_sin_f32_e32 v21, v17
	v_add_f32_e32 v17, v54, v55
	v_mov_b32_e32 v55, v1
	s_nop 0
	v_add_f32_dpp v17, v17, v17 quad_perm:[1,0,3,2] row_mask:0xf bank_mask:0xf bound_ctrl:1
	s_nop 1
	v_add_f32_dpp v17, v17, v17 quad_perm:[2,3,0,1] row_mask:0xf bank_mask:0xf bound_ctrl:1
	s_nop 1
	v_add_f32_dpp v17, v17, v17 row_ror:4 row_mask:0xf bank_mask:0xf bound_ctrl:1
	s_nop 1
	v_add_f32_dpp v17, v17, v17 row_ror:8 row_mask:0xf bank_mask:0xf bound_ctrl:1
	v_fmamk_f32 v17, v17, 0x3c800000, v237
	v_rsq_f32_e32 v23, v17
	s_nop 0
	v_mul_f32_e32 v17, v23, v52
	v_mul_f32_e32 v17, v0, v17
	ds_swizzle_b32 v52, v17 offset:swizzle(SWAP,4)
	v_mul_f32_e32 v205, v23, v46
	s_waitcnt lgkmcnt(0)
	v_mul_f32_e32 v52, v56, v52
	v_cndmask_b32_e64 v52, v52, -v52, s[36:37]
	v_fmac_f32_e32 v52, v51, v17
	v_cndmask_b32_e64 v54, v52, v17, s[40:41]
	v_pk_mul_f32 v[54:55], v[54:55], v[204:205]
	ds_swizzle_b32 v17, v55 offset:swizzle(SWAP,4)
	v_mul_f32_e32 v205, v23, v53
	v_cndmask_b32_e64 v46, v54, v54, s[40:41]
	v_cndmask_b32_e64 v46, v46, v46, s[40:41]
	v_cndmask_b32_e64 v46, v46, v46, s[40:41]
	s_waitcnt lgkmcnt(0)
	v_mul_f32_e32 v17, v50, v17
	v_cndmask_b32_e64 v17, v17, -v17, s[36:37]
	v_fmac_f32_e32 v17, v49, v55
	v_cndmask_b32_e64 v17, v17, v55, s[40:41]
	v_pk_mov_b32 v[52:53], v[16:17], v[2:3] op_sel:[1,0]
	s_nop 0
	v_pk_mul_f32 v[52:53], v[52:53], v[204:205]
	ds_swizzle_b32 v54, v53 offset:swizzle(SWAP,4)
	v_mov_b32_e32 v17, v52
	v_cndmask_b32_e64 v17, v17, v52, s[40:41]
	v_mul_f32_e32 v205, v23, v47
	s_waitcnt lgkmcnt(0)
	v_mul_f32_e32 v54, v48, v54
	v_cndmask_b32_e64 v54, v54, -v54, s[36:37]
	v_fmac_f32_e32 v54, v25, v53
	v_cndmask_b32_e64 v52, v54, v53, s[40:41]
	v_mov_b32_e32 v53, v3
	v_pk_mul_f32 v[52:53], v[52:53], v[204:205]
	ds_swizzle_b32 v23, v53 offset:swizzle(SWAP,4)
	v_cndmask_b32_e64 v47, v52, v52, s[40:41]
	v_cndmask_b32_e64 v52, v17, v17, s[40:41]
	v_cvt_pk_bf16_f32 v46, v46, v52
	s_waitcnt lgkmcnt(0)
	v_mul_f32_e32 v23, v21, v23
	v_cndmask_b32_e64 v23, v23, -v23, s[36:37]
	v_fmac_f32_e32 v23, v9, v53
	v_cndmask_b32_e64 v17, v23, v53, s[40:41]
	v_mul_f32_e32 v17, 0x3e38aa3b, v17
	v_mov_b32_e32 v23, v161
	v_cvt_pk_bf16_f32 v47, v47, v17
	v_lshl_add_u64 v[52:53], v[34:35], 0, v[22:23]
	global_store_dwordx2 v[52:53], v[46:47], off offset:512
	v_lshlrev_b32_e32 v47, 16, v45
	v_lshlrev_b32_e32 v46, 16, v44
	v_and_b32_e32 v45, 0xffff0000, v45
	v_and_b32_e32 v44, 0xffff0000, v44
	v_pk_mul_f32 v[52:53], v[44:45], v[44:45]
	s_nop 0
	v_pk_fma_f32 v[52:53], v[46:47], v[46:47], v[52:53]
	s_nop 0
	v_add_f32_e32 v17, v52, v53
	v_mov_b32_e32 v53, v1
	s_nop 0
	v_add_f32_dpp v17, v17, v17 quad_perm:[1,0,3,2] row_mask:0xf bank_mask:0xf bound_ctrl:1
	s_nop 1
	v_add_f32_dpp v17, v17, v17 quad_perm:[2,3,0,1] row_mask:0xf bank_mask:0xf bound_ctrl:1
	s_nop 1
	v_add_f32_dpp v17, v17, v17 row_ror:4 row_mask:0xf bank_mask:0xf bound_ctrl:1
	s_nop 1
	v_add_f32_dpp v17, v17, v17 row_ror:8 row_mask:0xf bank_mask:0xf bound_ctrl:1
	v_fmamk_f32 v17, v17, 0x3c800000, v237
	v_rsq_f32_e32 v23, v17
	s_nop 0
	v_mul_f32_e32 v17, v23, v46
	v_mul_f32_e32 v17, v0, v17
	ds_swizzle_b32 v46, v17 offset:swizzle(SWAP,4)
	v_mul_f32_e32 v205, v23, v44
	s_waitcnt lgkmcnt(0)
	v_mul_f32_e32 v46, v56, v46
	v_cndmask_b32_e64 v46, v46, -v46, s[36:37]
	v_fmac_f32_e32 v46, v51, v17
	v_cndmask_b32_e64 v52, v46, v17, s[40:41]
	v_pk_mul_f32 v[52:53], v[52:53], v[204:205]
	ds_swizzle_b32 v17, v53 offset:swizzle(SWAP,4)
	v_mul_f32_e32 v205, v23, v47
	v_cndmask_b32_e64 v44, v52, v52, s[40:41]
	v_cndmask_b32_e64 v44, v44, v44, s[40:41]
	v_cndmask_b32_e64 v44, v44, v44, s[40:41]
	s_waitcnt lgkmcnt(0)
	v_mul_f32_e32 v17, v50, v17
	v_cndmask_b32_e64 v17, v17, -v17, s[36:37]
	v_fmac_f32_e32 v17, v49, v53
	v_cndmask_b32_e64 v17, v17, v53, s[40:41]
	v_pk_mov_b32 v[46:47], v[16:17], v[2:3] op_sel:[1,0]
	s_nop 0
	v_pk_mul_f32 v[46:47], v[46:47], v[204:205]
	ds_swizzle_b32 v52, v47 offset:swizzle(SWAP,4)
	v_mov_b32_e32 v17, v46
	v_cndmask_b32_e64 v17, v17, v46, s[40:41]
	v_mul_f32_e32 v205, v23, v45
	v_cndmask_b32_e64 v17, v17, v17, s[40:41]
	s_waitcnt lgkmcnt(0)
	v_mul_f32_e32 v52, v48, v52
	v_cndmask_b32_e64 v52, v52, -v52, s[36:37]
	v_fmac_f32_e32 v52, v25, v47
	v_cndmask_b32_e64 v46, v52, v47, s[40:41]
	v_mov_b32_e32 v47, v3
	v_pk_mul_f32 v[46:47], v[46:47], v[204:205]
	ds_swizzle_b32 v23, v47 offset:swizzle(SWAP,4)
	v_cndmask_b32_e64 v45, v46, v46, s[40:41]
	v_cvt_pk_bf16_f32 v44, v44, v17
	v_mov_b32_e32 v17, v161
	s_waitcnt lgkmcnt(0)
	v_mul_f32_e32 v23, v21, v23
	v_cndmask_b32_e64 v23, v23, -v23, s[36:37]
	v_fmac_f32_e32 v23, v9, v47
	v_cndmask_b32_e64 v23, v23, v47, s[40:41]
	v_mul_f32_e32 v23, 0x3e38aa3b, v23
	v_cvt_pk_bf16_f32 v45, v45, v23
	v_lshl_add_u64 v[46:47], v[34:35], 0, v[16:17]
	global_store_dwordx2 v[46:47], v[44:45], off offset:512
	v_lshlrev_b32_e32 v45, 16, v39
	v_lshlrev_b32_e32 v44, 16, v38
	v_and_b32_e32 v39, 0xffff0000, v39
	v_and_b32_e32 v38, 0xffff0000, v38
	v_pk_mul_f32 v[46:47], v[38:39], v[38:39]
	s_nop 0
	v_pk_fma_f32 v[46:47], v[44:45], v[44:45], v[46:47]
	s_nop 0
	v_add_f32_e32 v17, v46, v47
	s_nop 1
	v_add_f32_dpp v17, v17, v17 quad_perm:[1,0,3,2] row_mask:0xf bank_mask:0xf bound_ctrl:1
	s_nop 1
	v_add_f32_dpp v17, v17, v17 quad_perm:[2,3,0,1] row_mask:0xf bank_mask:0xf bound_ctrl:1
	s_nop 1
	v_add_f32_dpp v17, v17, v17 row_ror:4 row_mask:0xf bank_mask:0xf bound_ctrl:1
	s_nop 1
	v_add_f32_dpp v17, v17, v17 row_ror:8 row_mask:0xf bank_mask:0xf bound_ctrl:1
	v_fmamk_f32 v17, v17, 0x3c800000, v237
	v_rsq_f32_e32 v46, v17
	s_nop 0
	v_mul_f32_e32 v17, v46, v44
	v_mul_f32_e32 v17, v4, v17
	ds_swizzle_b32 v23, v17 offset:swizzle(SWAP,4)
	s_waitcnt lgkmcnt(0)
	v_mul_f32_e32 v23, v56, v23
	v_cndmask_b32_e64 v23, v23, -v23, s[36:37]
	v_fmac_f32_e32 v23, v51, v17
	v_cndmask_b32_e64 v17, v23, v17, s[40:41]
	v_mul_f32_e32 v23, v46, v38
	v_mul_f32_e32 v23, v5, v23
	ds_swizzle_b32 v38, v23 offset:swizzle(SWAP,4)
	s_waitcnt lgkmcnt(0)
	v_mul_f32_e32 v38, v50, v38
	v_cndmask_b32_e64 v38, v38, -v38, s[36:37]
	v_fmac_f32_e32 v38, v49, v23
	v_cndmask_b32_e64 v23, v38, v23, s[40:41]
	v_mul_f32_e32 v38, v46, v45
	v_mul_f32_e32 v38, v6, v38
	ds_swizzle_b32 v44, v38 offset:swizzle(SWAP,4)
	s_waitcnt lgkmcnt(0)
	v_mul_f32_e32 v44, v48, v44
	v_cndmask_b32_e64 v44, v44, -v44, s[36:37]
	v_fmac_f32_e32 v44, v25, v38
	v_cndmask_b32_e64 v25, v44, v38, s[40:41]
	v_mul_f32_e32 v38, v46, v39
	v_mul_f32_e32 v38, v7, v38
	ds_swizzle_b32 v39, v38 offset:swizzle(SWAP,4)
	s_waitcnt lgkmcnt(0)
	v_mul_f32_e32 v21, v21, v39
	v_cndmask_b32_e64 v21, v21, -v21, s[36:37]
	v_fmac_f32_e32 v21, v9, v38
	v_cndmask_b32_e64 v9, v21, v38, s[40:41]
	s_and_saveexec_b64 s[0:1], vcc
	s_cbranch_execz .LBB0_452
	v_cvt_pk_bf16_f32 v39, v25, v9
	v_mov_b32_e32 v25, v161
	v_cvt_pk_bf16_f32 v38, v17, v23
	v_lshl_add_u64 v[34:35], v[34:35], 0, v[24:25]
	global_store_dwordx2 v[34:35], v[38:39], off offset:512
	s_branch .LBB0_452
.LBB0_475:
	s_andn2_saveexec_b64 s[28:29], s[28:29]
	s_cbranch_execz .LBB0_500
	v_mov_b32_e32 v0, 0xfffff340
	v_mov_b32_e32 v1, -1
	v_mad_u64_u32 v[8:9], s[0:1], v81, 11, v[0:1]
	v_mov_b32_e32 v9, v236
	v_readlane_b32 s4, v255, 11
	v_and_b32_e32 v17, 15, v9
	v_bfe_u32 v19, v9, 4, 2
	v_lshlrev_b32_e32 v21, 2, v17
	v_lshlrev_b32_e32 v12, 6, v19
	v_or_b32_e32 v23, 8, v19
	v_readlane_b32 s5, v255, 12
	v_or_b32_e32 v20, 0x100, v21
	v_min_u32_e32 v0, 9, v23
	v_mov_b64_e32 v[10:11], s[4:5]
	s_movk_i32 s0, 0x1200
	v_or_b32_e32 v22, v12, v21
	v_or_b32_e32 v16, v12, v20
	v_lshlrev_b32_e32 v25, 6, v0
	v_mad_u64_u32 v[10:11], s[0:1], v8, s0, v[10:11]
	v_lshlrev_b32_e32 v160, 1, v22
	v_lshl_add_u64 v[12:13], v[10:11], 0, v[160:161]
	v_lshlrev_b32_e32 v160, 1, v16
	v_or_b32_e32 v24, v25, v21
	v_lshlrev_b32_e32 v4, 4, v17
	v_lshl_add_u64 v[14:15], v[10:11], 0, v[160:161]
	v_lshlrev_b32_e32 v160, 1, v24
	global_load_dwordx4 v[0:3], v4, s[18:19]
	s_nop 0
	global_load_dwordx4 v[4:7], v4, s[18:19] offset:1024
	v_lshl_add_u64 v[10:11], v[10:11], 0, v[160:161]
	global_load_dwordx2 v[46:47], v[12:13], off offset:512
	global_load_dwordx2 v[44:45], v[14:15], off offset:512
	global_load_dwordx2 v[38:39], v[10:11], off offset:512
	v_and_b32_e32 v10, 63, v9
	v_and_b32_e32 v9, 4, v9
	v_cmp_eq_u32_e64 s[36:37], 0, v9
	v_and_b32_e32 v9, 12, v21
	v_cvt_f32_ubyte0_e32 v14, v9
	v_mul_f32_e32 v14, 0xbf549a78, v14
	v_exp_f32_e32 v59, v14
	v_or_b32_e32 v14, 1, v9
	v_cvt_f32_ubyte0_e32 v14, v14
	v_mul_f32_e32 v14, 0xbf549a78, v14
	v_exp_f32_e32 v60, v14
	v_or_b32_e32 v14, 2, v9
	v_or_b32_e32 v9, 3, v9
	v_cvt_f32_ubyte0_e32 v14, v14
	v_cvt_f32_ubyte0_e32 v9, v9
	v_mul_f32_e32 v14, 0xbf549a78, v14
	v_mul_f32_e32 v9, 0xbf549a78, v9
	v_exp_f32_e32 v61, v14
	v_exp_f32_e32 v62, v9
	v_readlane_b32 s0, v254, 28
	v_add_u32_e32 v18, 0x100, v16
	v_or_b32_e32 v20, v25, v20
	v_mov_b32_e32 v64, 0
	v_lshlrev_b32_e32 v160, 3, v10
	v_readlane_b32 s1, v254, 29
	v_cmp_gt_u32_e32 vcc, 10, v23
	v_lshlrev_b32_e64 v58, v19, 1
	v_lshl_add_u64 v[10:11], s[4:5], 0, v[160:161]
	v_cmp_gt_u32_e64 s[38:39], 8, v17
	v_lshl_add_u64 v[12:13], s[2:3], 0, v[160:161]
	v_lshl_add_u64 v[14:15], s[0:1], 0, v[160:161]
	s_mov_b32 s10, 0
	v_lshlrev_b32_e32 v16, 1, v16
	v_lshlrev_b32_e32 v18, 1, v18
	v_lshlrev_b32_e32 v20, 1, v20
	v_lshlrev_b32_e32 v22, 1, v22
	v_lshlrev_b32_e32 v24, 1, v24
	v_mov_b32_e32 v63, v8
	v_mov_b32_e32 v23, 0
	v_mov_b32_e32 v40, 0
	v_mov_b32_e32 v41, v64
	v_mov_b32_e32 v42, 0
	v_mov_b32_e32 v43, v64
	s_waitcnt vmcnt(0)
	s_branch .LBB0_478
.LBB0_477:
	s_or_b64 exec, exec, s[0:1]
	v_sub_u32_e32 v9, v19, v64
	v_cvt_f32_i32_e32 v9, v9
	v_lshlrev_b32_e32 v38, 16, v36
	v_and_b32_e32 v39, 0xffff0000, v36
	s_add_i32 s10, s10, 1
	v_rcp_iflag_f32_e32 v34, v9
	v_lshlrev_b64 v[26:27], 11, v[26:27]
	v_lshl_add_u64 v[26:27], v[12:13], 0, v[26:27]
	v_add_u32_e32 v63, 1, v63
	v_pk_fma_f32 v[38:39], v[34:35], v[42:43], v[38:39] op_sel_hi:[0,1,1] neg_lo:[0,0,1] neg_hi:[0,0,1]
	v_cvt_pk_bf16_f32 v36, v38, v39
	v_lshlrev_b32_e32 v38, 16, v37
	v_and_b32_e32 v39, 0xffff0000, v37
	v_pk_fma_f32 v[34:35], v[34:35], v[40:41], v[38:39] op_sel_hi:[0,1,1] neg_lo:[0,0,1] neg_hi:[0,0,1]
	v_cvt_pk_bf16_f32 v37, v34, v35
	s_cmp_eq_u32 s10, 11
	v_mov_b32_e32 v23, v19
	v_mov_b32_e32 v46, v28
	v_mov_b32_e32 v47, v29
	v_mov_b32_e32 v44, v30
	v_mov_b32_e32 v45, v31
	v_mov_b32_e32 v38, v32
	v_mov_b32_e32 v39, v33
	global_store_dwordx2 v[26:27], v[36:37], off
	s_cbranch_scc1 .LBB0_500
.LBB0_478:
	v_readlane_b32 s0, v255, 11
	v_readlane_b32 s1, v255, 12
	v_add_u32_e32 v26, s10, v8
	s_cmp_gt_u32 s10, 9
	v_mov_b64_e32 v[28:29], s[0:1]
	s_movk_i32 s0, 0x1200
	v_mad_i64_i32 v[34:35], s[0:1], v26, s0, v[28:29]
	v_mov_b32_e32 v28, v46
	v_mov_b32_e32 v29, v47
	v_mov_b32_e32 v30, v44
	v_mov_b32_e32 v31, v45
	v_mov_b32_e32 v32, v38
	v_mov_b32_e32 v33, v39
	s_cbranch_scc1 .LBB0_480
	v_lshl_add_u64 v[28:29], v[34:35], 0, s[34:35]
	v_mov_b32_e32 v17, v161
	v_mov_b32_e32 v19, v161
	v_lshl_add_u64 v[30:31], v[28:29], 0, v[16:17]
	v_lshl_add_u64 v[32:33], v[28:29], 0, v[18:19]
	v_mov_b32_e32 v21, v161
	v_lshl_add_u64 v[36:37], v[28:29], 0, v[20:21]
	global_load_dwordx2 v[28:29], v[30:31], off
	s_nop 0
	global_load_dwordx2 v[30:31], v[32:33], off
	s_nop 0
	global_load_dwordx2 v[32:33], v[36:37], off

.LBB0_496:
	s_or_b64 exec, exec, s[6:7]
.LBB0_497:
	s_or_b64 exec, exec, s[4:5]
	s_waitcnt vmcnt(0)
.LBB0_498:
	s_or_b64 exec, exec, s[2:3]
	v_lshrrev_b32_e32 v9, 6, v9
	v_and_b32_e32 v17, 63, v26
	v_cndmask_b32_e64 v9, v17, v9, s[38:39]
	v_cvt_f32_ubyte0_e32 v9, v9
	v_mul_f32_e32 v17, v59, v9
	v_mul_f32_e32 v17, 0.15915494, v17
	v_cos_f32_e32 v51, v17
	v_sin_f32_e32 v56, v17
	v_mul_f32_e32 v17, v60, v9
	v_mul_f32_e32 v17, 0.15915494, v17
	v_cos_f32_e32 v49, v17
	v_sin_f32_e32 v50, v17
	v_mul_f32_e32 v17, v61, v9
	v_lshlrev_b32_e32 v53, 16, v47
	v_lshlrev_b32_e32 v52, 16, v46
	v_and_b32_e32 v47, 0xffff0000, v47
	v_and_b32_e32 v46, 0xffff0000, v46
	v_mul_f32_e32 v17, 0.15915494, v17
	v_mul_f32_e32 v9, v62, v9
	v_pk_mul_f32 v[54:55], v[46:47], v[46:47]
	v_cos_f32_e32 v25, v17
	v_sin_f32_e32 v48, v17
	v_mul_f32_e32 v17, 0.15915494, v9
	v_pk_fma_f32 v[54:55], v[52:53], v[52:53], v[54:55]
	v_cos_f32_e32 v9, v17
	v_sin_f32_e32 v21, v17
	v_add_f32_e32 v17, v54, v55
	v_mov_b32_e32 v55, v1
	s_nop 0
	v_add_f32_dpp v17, v17, v17 quad_perm:[1,0,3,2] row_mask:0xf bank_mask:0xf bound_ctrl:1
	s_nop 1
	v_add_f32_dpp v17, v17, v17 quad_perm:[2,3,0,1] row_mask:0xf bank_mask:0xf bound_ctrl:1
	s_nop 1
	v_add_f32_dpp v17, v17, v17 row_ror:4 row_mask:0xf bank_mask:0xf bound_ctrl:1
	s_nop 1
	v_add_f32_dpp v17, v17, v17 row_ror:8 row_mask:0xf bank_mask:0xf bound_ctrl:1
	v_fmamk_f32 v17, v17, 0x3c800000, v237
	v_rsq_f32_e32 v23, v17
	s_nop 0
	v_mul_f32_e32 v17, v23, v52
	v_mul_f32_e32 v17, v0, v17
	ds_swizzle_b32 v52, v17 offset:swizzle(SWAP,4)
	v_mul_f32_e32 v205, v23, v46
	s_waitcnt lgkmcnt(0)
	v_mul_f32_e32 v52, v56, v52
	v_cndmask_b32_e64 v52, v52, -v52, s[36:37]
	v_fmac_f32_e32 v52, v51, v17
	v_cndmask_b32_e64 v54, v52, v17, s[40:41]
	v_pk_mul_f32 v[54:55], v[54:55], v[204:205]
	ds_swizzle_b32 v17, v55 offset:swizzle(SWAP,4)
	v_mul_f32_e32 v205, v23, v53
	v_cndmask_b32_e64 v46, v54, v54, s[40:41]
	v_cndmask_b32_e64 v46, v46, v46, s[40:41]
	v_cndmask_b32_e64 v46, v46, v46, s[40:41]
	s_waitcnt lgkmcnt(0)
	v_mul_f32_e32 v17, v50, v17
	v_cndmask_b32_e64 v17, v17, -v17, s[36:37]
	v_fmac_f32_e32 v17, v49, v55
	v_cndmask_b32_e64 v17, v17, v55, s[40:41]
	v_pk_mov_b32 v[52:53], v[16:17], v[2:3] op_sel:[1,0]
	s_nop 0
	v_pk_mul_f32 v[52:53], v[52:53], v[204:205]
	ds_swizzle_b32 v54, v53 offset:swizzle(SWAP,4)
	v_mov_b32_e32 v17, v52
	v_cndmask_b32_e64 v17, v17, v52, s[40:41]
	v_mul_f32_e32 v205, v23, v47
	s_waitcnt lgkmcnt(0)
	v_mul_f32_e32 v54, v48, v54
	v_cndmask_b32_e64 v54, v54, -v54, s[36:37]
	v_fmac_f32_e32 v54, v25, v53
	v_cndmask_b32_e64 v52, v54, v53, s[40:41]
	v_mov_b32_e32 v53, v3
	v_pk_mul_f32 v[52:53], v[52:53], v[204:205]
	ds_swizzle_b32 v23, v53 offset:swizzle(SWAP,4)
	v_cndmask_b32_e64 v47, v52, v52, s[40:41]
	v_cndmask_b32_e64 v52, v17, v17, s[40:41]
	v_cvt_pk_bf16_f32 v46, v46, v52
	s_waitcnt lgkmcnt(0)
	v_mul_f32_e32 v23, v21, v23
	v_cndmask_b32_e64 v23, v23, -v23, s[36:37]
	v_fmac_f32_e32 v23, v9, v53
	v_cndmask_b32_e64 v17, v23, v53, s[40:41]
	v_mul_f32_e32 v17, 0x3e38aa3b, v17
	v_mov_b32_e32 v23, v161
	v_cvt_pk_bf16_f32 v47, v47, v17
	v_lshl_add_u64 v[52:53], v[34:35], 0, v[22:23]
	global_store_dwordx2 v[52:53], v[46:47], off offset:512
	v_lshlrev_b32_e32 v47, 16, v45
	v_lshlrev_b32_e32 v46, 16, v44
	v_and_b32_e32 v45, 0xffff0000, v45
	v_and_b32_e32 v44, 0xffff0000, v44
	v_pk_mul_f32 v[52:53], v[44:45], v[44:45]
	s_nop 0
	v_pk_fma_f32 v[52:53], v[46:47], v[46:47], v[52:53]
	s_nop 0
	v_add_f32_e32 v17, v52, v53
	v_mov_b32_e32 v53, v1
	s_nop 0
	v_add_f32_dpp v17, v17, v17 quad_perm:[1,0,3,2] row_mask:0xf bank_mask:0xf bound_ctrl:1
	s_nop 1
	v_add_f32_dpp v17, v17, v17 quad_perm:[2,3,0,1] row_mask:0xf bank_mask:0xf bound_ctrl:1
	s_nop 1
	v_add_f32_dpp v17, v17, v17 row_ror:4 row_mask:0xf bank_mask:0xf bound_ctrl:1
	s_nop 1
	v_add_f32_dpp v17, v17, v17 row_ror:8 row_mask:0xf bank_mask:0xf bound_ctrl:1
	v_fmamk_f32 v17, v17, 0x3c800000, v237
	v_rsq_f32_e32 v23, v17
	s_nop 0
	v_mul_f32_e32 v17, v23, v46
	v_mul_f32_e32 v17, v0, v17
	ds_swizzle_b32 v46, v17 offset:swizzle(SWAP,4)
	v_mul_f32_e32 v205, v23, v44
	s_waitcnt lgkmcnt(0)
	v_mul_f32_e32 v46, v56, v46
	v_cndmask_b32_e64 v46, v46, -v46, s[36:37]
	v_fmac_f32_e32 v46, v51, v17
	v_cndmask_b32_e64 v52, v46, v17, s[40:41]
	v_pk_mul_f32 v[52:53], v[52:53], v[204:205]
	ds_swizzle_b32 v17, v53 offset:swizzle(SWAP,4)
	v_mul_f32_e32 v205, v23, v47
	v_cndmask_b32_e64 v44, v52, v52, s[40:41]
	v_cndmask_b32_e64 v44, v44, v44, s[40:41]
	v_cndmask_b32_e64 v44, v44, v44, s[40:41]
	s_waitcnt lgkmcnt(0)
	v_mul_f32_e32 v17, v50, v17
	v_cndmask_b32_e64 v17, v17, -v17, s[36:37]
	v_fmac_f32_e32 v17, v49, v53
	v_cndmask_b32_e64 v17, v17, v53, s[40:41]
	v_pk_mov_b32 v[46:47], v[16:17], v[2:3] op_sel:[1,0]
	s_nop 0
	v_pk_mul_f32 v[46:47], v[46:47], v[204:205]
	ds_swizzle_b32 v52, v47 offset:swizzle(SWAP,4)
	v_mov_b32_e32 v17, v46
	v_cndmask_b32_e64 v17, v17, v46, s[40:41]
	v_mul_f32_e32 v205, v23, v45
	v_cndmask_b32_e64 v17, v17, v17, s[40:41]
	s_waitcnt lgkmcnt(0)
	v_mul_f32_e32 v52, v48, v52
	v_cndmask_b32_e64 v52, v52, -v52, s[36:37]
	v_fmac_f32_e32 v52, v25, v47
	v_cndmask_b32_e64 v46, v52, v47, s[40:41]
	v_mov_b32_e32 v47, v3
	v_pk_mul_f32 v[46:47], v[46:47], v[204:205]
	ds_swizzle_b32 v23, v47 offset:swizzle(SWAP,4)
	v_cndmask_b32_e64 v45, v46, v46, s[40:41]
	v_cvt_pk_bf16_f32 v44, v44, v17
	v_mov_b32_e32 v17, v161
	s_waitcnt lgkmcnt(0)
	v_mul_f32_e32 v23, v21, v23
	v_cndmask_b32_e64 v23, v23, -v23, s[36:37]
	v_fmac_f32_e32 v23, v9, v47
	v_cndmask_b32_e64 v23, v23, v47, s[40:41]
	v_mul_f32_e32 v23, 0x3e38aa3b, v23
	v_cvt_pk_bf16_f32 v45, v45, v23
	v_lshl_add_u64 v[46:47], v[34:35], 0, v[16:17]
	global_store_dwordx2 v[46:47], v[44:45], off offset:512
	v_lshlrev_b32_e32 v45, 16, v39
	v_lshlrev_b32_e32 v44, 16, v38
	v_and_b32_e32 v39, 0xffff0000, v39
	v_and_b32_e32 v38, 0xffff0000, v38
	v_pk_mul_f32 v[46:47], v[38:39], v[38:39]
	s_nop 0
	v_pk_fma_f32 v[46:47], v[44:45], v[44:45], v[46:47]
	s_nop 0
	v_add_f32_e32 v17, v46, v47
	s_nop 1
	v_add_f32_dpp v17, v17, v17 quad_perm:[1,0,3,2] row_mask:0xf bank_mask:0xf bound_ctrl:1
	s_nop 1
	v_add_f32_dpp v17, v17, v17 quad_perm:[2,3,0,1] row_mask:0xf bank_mask:0xf bound_ctrl:1
	s_nop 1
	v_add_f32_dpp v17, v17, v17 row_ror:4 row_mask:0xf bank_mask:0xf bound_ctrl:1
	s_nop 1
	v_add_f32_dpp v17, v17, v17 row_ror:8 row_mask:0xf bank_mask:0xf bound_ctrl:1
	v_fmamk_f32 v17, v17, 0x3c800000, v237
	v_rsq_f32_e32 v46, v17
	s_nop 0
	v_mul_f32_e32 v17, v46, v44
	v_mul_f32_e32 v17, v4, v17
	ds_swizzle_b32 v23, v17 offset:swizzle(SWAP,4)
	s_waitcnt lgkmcnt(0)
	v_mul_f32_e32 v23, v56, v23
	v_cndmask_b32_e64 v23, v23, -v23, s[36:37]
	v_fmac_f32_e32 v23, v51, v17
	v_cndmask_b32_e64 v17, v23, v17, s[40:41]
	v_mul_f32_e32 v23, v46, v38
	v_mul_f32_e32 v23, v5, v23
	ds_swizzle_b32 v38, v23 offset:swizzle(SWAP,4)
	s_waitcnt lgkmcnt(0)
	v_mul_f32_e32 v38, v50, v38
	v_cndmask_b32_e64 v38, v38, -v38, s[36:37]
	v_fmac_f32_e32 v38, v49, v23
	v_cndmask_b32_e64 v23, v38, v23, s[40:41]
	v_mul_f32_e32 v38, v46, v45
	v_mul_f32_e32 v38, v6, v38
	ds_swizzle_b32 v44, v38 offset:swizzle(SWAP,4)
	s_waitcnt lgkmcnt(0)
	v_mul_f32_e32 v44, v48, v44
	v_cndmask_b32_e64 v44, v44, -v44, s[36:37]
	v_fmac_f32_e32 v44, v25, v38
	v_cndmask_b32_e64 v25, v44, v38, s[40:41]
	v_mul_f32_e32 v38, v46, v39
	v_mul_f32_e32 v38, v7, v38
	ds_swizzle_b32 v39, v38 offset:swizzle(SWAP,4)
	s_waitcnt lgkmcnt(0)
	v_mul_f32_e32 v21, v21, v39
	v_cndmask_b32_e64 v21, v21, -v21, s[36:37]
	v_fmac_f32_e32 v21, v9, v38
	v_cndmask_b32_e64 v9, v21, v38, s[40:41]
	s_and_saveexec_b64 s[0:1], vcc
	s_cbranch_execz .LBB0_477
	v_cvt_pk_bf16_f32 v39, v25, v9
	v_mov_b32_e32 v25, v161
	v_cvt_pk_bf16_f32 v38, v17, v23
	v_lshl_add_u64 v[34:35], v[34:35], 0, v[24:25]
	global_store_dwordx2 v[34:35], v[38:39], off offset:512
	s_branch .LBB0_477

.LBB0_501:
	s_andn2_saveexec_b64 s[2:3], s[16:17]
	s_cbranch_execz .LBB0_530
	v_add_u32_e32 v4, 0xffffff00, v81
	s_mov_b32 s0, 0xe38f
	v_mul_u32_u24_sdwa v1, v4, s0 dst_sel:DWORD dst_unused:UNUSED_PAD src0_sel:WORD_0 src1_sel:DWORD
	v_lshrrev_b32_e32 v2, 21, v1
	v_mul_lo_u16_e32 v3, 36, v2
	v_sub_u16_e32 v3, v4, v3
	v_mov_b32_e32 v0, v236
	v_lshrrev_b32_e32 v5, 22, v1
	v_cmp_lt_u16_e32 vcc, 31, v3
	v_lshlrev_b16_e32 v3, 6, v3
	s_and_saveexec_b64 s[0:1], vcc
	s_xor_b64 s[0:1], exec, s[0:1]
	v_lshlrev_b32_e32 v1, 8, v5
	s_movk_i32 s4, 0x3800
	v_add3_u32 v1, v3, v1, s4
	s_andn2_saveexec_b64 s[0:1], s[0:1]
	v_lshl_or_b32 v1, v5, 11, v3
	s_or_b64 exec, exec, s[0:1]
	v_readlane_b32 s8, v254, 28
	v_readlane_b32 s9, v254, 29
	s_movk_i32 s6, 0x1200
	v_lshlrev_b32_e32 v8, 7, v2
	v_mov_b64_e32 v[6:7], s[8:9]
	v_and_b32_e32 v5, 63, v0
	v_mad_u64_u32 v[0:1], s[0:1], v1, s6, v[6:7]
	v_and_b32_e32 v160, 0x80, v8
	v_lshl_add_u64 v[0:1], v[0:1], 0, v[160:161]
	v_lshlrev_b32_e32 v160, 1, v5
	v_lshl_add_u64 v[0:1], v[0:1], 0, v[160:161]
	s_mov_b32 s0, 0xb200000
	v_add_co_u32_e32 v8, vcc, s0, v0
	s_mov_b32 s0, 0xb201000
	s_nop 0
	v_addc_co_u32_e32 v9, vcc, 0, v1, vcc
	v_add_co_u32_e32 v10, vcc, s0, v0
	s_mov_b32 s0, 0xb202000
	s_nop 0
	v_addc_co_u32_e32 v11, vcc, 0, v1, vcc
	v_add_co_u32_e32 v12, vcc, s0, v0
	s_mov_b32 s0, 0xb203000
	s_nop 0
	v_addc_co_u32_e32 v13, vcc, 0, v1, vcc
	v_add_co_u32_e32 v14, vcc, s0, v0
	s_mov_b32 s0, 0xb204000
	s_nop 0
	v_addc_co_u32_e32 v15, vcc, 0, v1, vcc
	v_add_co_u32_e32 v16, vcc, s0, v0
	s_mov_b32 s0, 0xb206000
	s_nop 0
	v_addc_co_u32_e32 v17, vcc, 0, v1, vcc
	v_add_co_u32_e32 v18, vcc, s0, v0
	s_mov_b32 s0, 0xb207000
	s_nop 0
	v_addc_co_u32_e32 v19, vcc, 0, v1, vcc
	v_add_co_u32_e32 v20, vcc, s0, v0
	s_mov_b32 s0, 0xb208000
	s_nop 0
	v_addc_co_u32_e32 v21, vcc, 0, v1, vcc
	v_add_co_u32_e32 v22, vcc, s0, v0
	v_lshl_or_b32 v2, v2, 6, v5
	s_nop 0
	v_addc_co_u32_e32 v23, vcc, 0, v1, vcc
	global_load_ushort v8, v[8:9], off offset:1792
	s_nop 0
	global_load_ushort v9, v[10:11], off offset:2304
	global_load_ushort v24, v[12:13], off offset:2816
	global_load_ushort v25, v[14:15], off offset:3328
	global_load_ushort v26, v[16:17], off offset:3840
	global_load_ushort v27, v[18:19], off offset:256
	global_load_ushort v28, v[20:21], off offset:768
	global_load_ushort v29, v[22:23], off offset:1280
	v_mad_u64_u32 v[6:7], s[0:1], v2, s6, v[6:7]
	s_mov_b32 s0, 0xb209000
	s_nop 0
	v_add_co_u32_e32 v10, vcc, s0, v0
	s_mov_b32 s0, 0xb20a000
	s_nop 0
	v_addc_co_u32_e32 v11, vcc, 0, v1, vcc
	v_add_co_u32_e32 v12, vcc, s0, v0
	s_mov_b32 s0, 0xb20b000
	s_nop 0
	v_addc_co_u32_e32 v13, vcc, 0, v1, vcc
	v_add_co_u32_e32 v14, vcc, s0, v0
	s_mov_b32 s0, 0xb20c000
	s_nop 0
	v_addc_co_u32_e32 v15, vcc, 0, v1, vcc
	v_add_co_u32_e32 v16, vcc, s0, v0
	s_mov_b32 s0, 0xb20d000
	s_nop 0
	v_addc_co_u32_e32 v17, vcc, 0, v1, vcc
	v_add_co_u32_e32 v18, vcc, s0, v0
	s_mov_b32 s0, 0xb20f000
	s_nop 0
	v_addc_co_u32_e32 v19, vcc, 0, v1, vcc
	v_lshlrev_b32_e32 v160, 1, v3
	v_add_co_u32_e32 v20, vcc, s0, v0
	v_lshl_add_u64 v[2:3], v[6:7], 0, v[160:161]
	s_nop 0
	v_addc_co_u32_e32 v21, vcc, 0, v1, vcc
	s_mov_b32 s0, 0x19300000
	v_add_co_u32_e32 v22, vcc, s0, v2
	s_mov_b32 s0, 0xb210000
	s_nop 0
	v_addc_co_u32_e32 v23, vcc, 0, v3, vcc
	v_readlane_b32 s10, v255, 11
	v_readlane_b32 s11, v255, 12
	v_mov_b32_e32 v60, 0
	s_mov_b32 s14, 0
	v_mov_b32_e32 v38, 0
	v_mov_b32_e32 v39, v60
	v_mov_b32_e32 v36, 0
	v_mov_b32_e32 v37, v60
	s_waitcnt vmcnt(0)
	v_lshl_or_b32 v6, v9, 16, v8
	v_lshl_or_b32 v7, v25, 16, v24
	v_lshl_or_b32 v8, v27, 16, v26
	v_lshl_or_b32 v9, v29, 16, v28
	global_store_dwordx4 v[22:23], v[6:9], off
	s_nop 1
	v_add_co_u32_e32 v6, vcc, s0, v0
	s_mov_b32 s0, 0xb211000
	s_nop 0
	v_addc_co_u32_e32 v7, vcc, 0, v1, vcc
	v_add_co_u32_e32 v8, vcc, s0, v0
	s_mov_b32 s0, 0xb212000
	s_nop 0
	v_addc_co_u32_e32 v9, vcc, 0, v1, vcc
	global_load_ushort v5, v[10:11], off offset:1792
	global_load_ushort v26, v[12:13], off offset:2304
	global_load_ushort v27, v[14:15], off offset:2816
	global_load_ushort v28, v[16:17], off offset:3328
	global_load_ushort v29, v[18:19], off offset:3840
	global_load_ushort v30, v[20:21], off offset:256
	global_load_ushort v31, v[6:7], off offset:768
	s_nop 0
	global_load_ushort v9, v[8:9], off offset:1280
	v_add_co_u32_e32 v10, vcc, s0, v0
	s_mov_b32 s0, 0xb213000
	s_nop 0
	v_addc_co_u32_e32 v11, vcc, 0, v1, vcc
	v_add_co_u32_e32 v12, vcc, s0, v0
	s_mov_b32 s0, 0xb214000
	s_nop 0
	v_addc_co_u32_e32 v13, vcc, 0, v1, vcc
	v_add_co_u32_e32 v14, vcc, s0, v0
	s_mov_b32 s0, 0xb215000
	s_nop 0
	v_addc_co_u32_e32 v15, vcc, 0, v1, vcc
	v_add_co_u32_e32 v16, vcc, s0, v0
	s_mov_b32 s0, 0xb216000
	s_nop 0
	v_addc_co_u32_e32 v17, vcc, 0, v1, vcc
	v_add_co_u32_e32 v18, vcc, s0, v0
	s_mov_b32 s0, 0xb218000
	s_nop 0
	v_addc_co_u32_e32 v19, vcc, 0, v1, vcc
	v_add_co_u32_e32 v20, vcc, s0, v0
	s_mov_b32 s0, 0xb219000
	s_nop 0
	v_addc_co_u32_e32 v21, vcc, 0, v1, vcc
	v_add_co_u32_e32 v22, vcc, s0, v0
	s_mov_b32 s0, 0xb21a000
	s_nop 0
	v_addc_co_u32_e32 v23, vcc, 0, v1, vcc
	v_add_co_u32_e32 v24, vcc, s0, v0
	s_mov_b64 s[0:1], 0x19300000
	v_lshl_add_u64 v[2:3], v[2:3], 0, s[0:1]
	v_addc_co_u32_e32 v25, vcc, 0, v1, vcc
	s_mov_b32 s0, 0xb21b000
	s_waitcnt vmcnt(0)
	v_lshl_or_b32 v6, v26, 16, v5
	v_lshl_or_b32 v7, v28, 16, v27
	v_lshl_or_b32 v8, v30, 16, v29
	v_lshl_or_b32 v9, v9, 16, v31
	global_store_dwordx4 v[2:3], v[6:9], off offset:16
	global_load_ushort v5, v[10:11], off offset:1792
	s_nop 0
	global_load_ushort v6, v[12:13], off offset:2304
	global_load_ushort v7, v[14:15], off offset:2816
	global_load_ushort v8, v[16:17], off offset:3328
	global_load_ushort v9, v[18:19], off offset:3840
	global_load_ushort v26, v[20:21], off offset:256
	global_load_ushort v27, v[22:23], off offset:768
	global_load_ushort v28, v[24:25], off offset:1280
	v_add_co_u32_e32 v10, vcc, s0, v0
	s_mov_b32 s0, 0xb21c000
	s_nop 0
	v_addc_co_u32_e32 v11, vcc, 0, v1, vcc
	v_add_co_u32_e32 v12, vcc, s0, v0
	s_mov_b32 s0, 0xb21d000
	s_nop 0
	v_addc_co_u32_e32 v13, vcc, 0, v1, vcc
	v_add_co_u32_e32 v14, vcc, s0, v0
	s_mov_b32 s0, 0xb21e000
	s_nop 0
	v_addc_co_u32_e32 v15, vcc, 0, v1, vcc
	v_add_co_u32_e32 v16, vcc, s0, v0
	s_mov_b32 s0, 0xb21f000
	s_nop 0
	v_addc_co_u32_e32 v17, vcc, 0, v1, vcc
	v_add_co_u32_e32 v18, vcc, s0, v0
	s_mov_b32 s0, 0xb221000
	s_nop 0
	v_addc_co_u32_e32 v19, vcc, 0, v1, vcc
	v_add_co_u32_e32 v20, vcc, s0, v0
	s_mov_b32 s0, 0xb222000
	s_nop 0
	v_addc_co_u32_e32 v21, vcc, 0, v1, vcc
	v_add_co_u32_e32 v22, vcc, s0, v0
	s_mov_b32 s0, 0xb223000
	s_nop 0
	v_addc_co_u32_e32 v23, vcc, 0, v1, vcc
	v_add_co_u32_e32 v24, vcc, s0, v0
	s_mov_b32 s0, 0xb224000
	s_nop 0
	v_addc_co_u32_e32 v25, vcc, 0, v1, vcc
	s_waitcnt vmcnt(0)
	v_lshl_or_b32 v6, v6, 16, v5
	v_lshl_or_b32 v7, v8, 16, v7
	v_lshl_or_b32 v8, v26, 16, v9
	v_lshl_or_b32 v9, v28, 16, v27
	global_store_dwordx4 v[2:3], v[6:9], off offset:32
	global_load_ushort v5, v[10:11], off offset:1792
	s_nop 0
	global_load_ushort v6, v[12:13], off offset:2304
	global_load_ushort v7, v[14:15], off offset:2816
	global_load_ushort v8, v[16:17], off offset:3328
	global_load_ushort v9, v[18:19], off offset:3840
	global_load_ushort v26, v[20:21], off offset:256
	global_load_ushort v27, v[22:23], off offset:768
	global_load_ushort v28, v[24:25], off offset:1280
	v_add_co_u32_e32 v10, vcc, s0, v0
	s_mov_b32 s0, 0xb225000
	s_nop 0
	v_addc_co_u32_e32 v11, vcc, 0, v1, vcc
	v_add_co_u32_e32 v12, vcc, s0, v0
	s_mov_b32 s0, 0xb226000
	s_nop 0
	v_addc_co_u32_e32 v13, vcc, 0, v1, vcc
	v_add_co_u32_e32 v14, vcc, s0, v0
	s_mov_b32 s0, 0xb227000
	s_nop 0
	v_addc_co_u32_e32 v15, vcc, 0, v1, vcc
	v_add_co_u32_e32 v16, vcc, s0, v0
	s_mov_b32 s0, 0xb228000
	s_nop 0
	v_addc_co_u32_e32 v17, vcc, 0, v1, vcc
	v_add_co_u32_e32 v18, vcc, s0, v0
	s_mov_b32 s0, 0xb22a000
	s_nop 0
	v_addc_co_u32_e32 v19, vcc, 0, v1, vcc
	v_add_co_u32_e32 v20, vcc, s0, v0
	s_mov_b32 s0, 0xb22b000
	s_nop 0
	v_addc_co_u32_e32 v21, vcc, 0, v1, vcc
	v_add_co_u32_e32 v22, vcc, s0, v0
	s_mov_b32 s0, 0xb22c000
	s_nop 0
	v_addc_co_u32_e32 v23, vcc, 0, v1, vcc
	v_add_co_u32_e32 v24, vcc, s0, v0
	s_mov_b32 s0, 0xb22d000
	s_nop 0
	v_addc_co_u32_e32 v25, vcc, 0, v1, vcc
	s_waitcnt vmcnt(0)
	v_lshl_or_b32 v6, v6, 16, v5
	v_lshl_or_b32 v7, v8, 16, v7
	v_lshl_or_b32 v8, v26, 16, v9
	v_lshl_or_b32 v9, v28, 16, v27
	global_store_dwordx4 v[2:3], v[6:9], off offset:48
	global_load_ushort v5, v[10:11], off offset:1792
	s_nop 0
	global_load_ushort v6, v[12:13], off offset:2304
	global_load_ushort v7, v[14:15], off offset:2816
	global_load_ushort v8, v[16:17], off offset:3328
	global_load_ushort v9, v[18:19], off offset:3840
	global_load_ushort v26, v[20:21], off offset:256
	global_load_ushort v27, v[22:23], off offset:768
	global_load_ushort v28, v[24:25], off offset:1280
	v_add_co_u32_e32 v10, vcc, s0, v0
	s_mov_b32 s0, 0xb22e000
	s_nop 0
	v_addc_co_u32_e32 v11, vcc, 0, v1, vcc
	v_add_co_u32_e32 v12, vcc, s0, v0
	s_mov_b32 s0, 0xb22f000
	s_nop 0
	v_addc_co_u32_e32 v13, vcc, 0, v1, vcc
	v_add_co_u32_e32 v14, vcc, s0, v0
	s_mov_b32 s0, 0xb230000
	s_nop 0
	v_addc_co_u32_e32 v15, vcc, 0, v1, vcc
	v_add_co_u32_e32 v16, vcc, s0, v0
	s_mov_b32 s0, 0xb231000
	s_nop 0
	v_addc_co_u32_e32 v17, vcc, 0, v1, vcc
	v_add_co_u32_e32 v18, vcc, s0, v0
	s_mov_b32 s0, 0xb233000
	s_nop 0
	v_addc_co_u32_e32 v19, vcc, 0, v1, vcc
	v_add_co_u32_e32 v20, vcc, s0, v0
	s_mov_b32 s0, 0xb234000
	s_nop 0
	v_addc_co_u32_e32 v21, vcc, 0, v1, vcc
	v_add_co_u32_e32 v22, vcc, s0, v0
	s_mov_b32 s0, 0xb235000
	s_nop 0
	v_addc_co_u32_e32 v23, vcc, 0, v1, vcc
	v_add_co_u32_e32 v24, vcc, s0, v0
	s_mov_b32 s0, 0xb236000
	s_nop 0
	v_addc_co_u32_e32 v25, vcc, 0, v1, vcc
	s_waitcnt vmcnt(0)
	v_lshl_or_b32 v6, v6, 16, v5
	v_lshl_or_b32 v7, v8, 16, v7
	v_lshl_or_b32 v8, v26, 16, v9
	v_lshl_or_b32 v9, v28, 16, v27
	global_store_dwordx4 v[2:3], v[6:9], off offset:64
	global_load_ushort v5, v[10:11], off offset:1792
	s_nop 0
	global_load_ushort v6, v[12:13], off offset:2304
	global_load_ushort v7, v[14:15], off offset:2816
	global_load_ushort v8, v[16:17], off offset:3328
	global_load_ushort v9, v[18:19], off offset:3840
	global_load_ushort v26, v[20:21], off offset:256
	global_load_ushort v27, v[22:23], off offset:768
	global_load_ushort v28, v[24:25], off offset:1280
	v_add_co_u32_e32 v10, vcc, s0, v0
	s_mov_b32 s0, 0xb237000
	s_nop 0
	v_addc_co_u32_e32 v11, vcc, 0, v1, vcc
	v_add_co_u32_e32 v12, vcc, s0, v0
	s_mov_b32 s0, 0xb238000
	s_nop 0
	v_addc_co_u32_e32 v13, vcc, 0, v1, vcc
	v_add_co_u32_e32 v14, vcc, s0, v0
	s_mov_b32 s0, 0xb239000
	s_nop 0
	v_addc_co_u32_e32 v15, vcc, 0, v1, vcc
	v_add_co_u32_e32 v16, vcc, s0, v0
	s_mov_b32 s0, 0xb23a000
	s_nop 0
	v_addc_co_u32_e32 v17, vcc, 0, v1, vcc
	v_add_co_u32_e32 v18, vcc, s0, v0
	s_mov_b32 s0, 0xb23c000
	s_nop 0
	v_addc_co_u32_e32 v19, vcc, 0, v1, vcc
	v_add_co_u32_e32 v20, vcc, s0, v0
	s_mov_b32 s0, 0xb23d000
	s_nop 0
	v_addc_co_u32_e32 v21, vcc, 0, v1, vcc
	v_add_co_u32_e32 v22, vcc, s0, v0
	s_mov_b32 s0, 0xb23e000
	s_nop 0
	v_addc_co_u32_e32 v23, vcc, 0, v1, vcc
	v_add_co_u32_e32 v24, vcc, s0, v0
	s_mov_b32 s0, 0xb23f000
	s_nop 0
	v_addc_co_u32_e32 v25, vcc, 0, v1, vcc
	s_waitcnt vmcnt(0)
	v_lshl_or_b32 v6, v6, 16, v5
	v_lshl_or_b32 v7, v8, 16, v7
	v_lshl_or_b32 v8, v26, 16, v9
	v_lshl_or_b32 v9, v28, 16, v27
	global_store_dwordx4 v[2:3], v[6:9], off offset:80
	global_load_ushort v5, v[10:11], off offset:1792
	s_nop 0
	global_load_ushort v6, v[12:13], off offset:2304
	global_load_ushort v7, v[14:15], off offset:2816
	global_load_ushort v8, v[16:17], off offset:3328
	global_load_ushort v9, v[18:19], off offset:3840
	global_load_ushort v26, v[20:21], off offset:256
	global_load_ushort v27, v[22:23], off offset:768
	s_nop 0
	global_load_ushort v24, v[24:25], off offset:1280
	v_add_co_u32_e32 v10, vcc, s0, v0
	s_mov_b32 s0, 0xb240000
	s_nop 0
	v_addc_co_u32_e32 v11, vcc, 0, v1, vcc
	v_add_co_u32_e32 v12, vcc, s0, v0
	s_mov_b32 s0, 0xb241000
	s_nop 0
	v_addc_co_u32_e32 v13, vcc, 0, v1, vcc
	v_add_co_u32_e32 v14, vcc, s0, v0
	s_mov_b32 s0, 0xb242000
	s_nop 0
	v_addc_co_u32_e32 v15, vcc, 0, v1, vcc
	v_add_co_u32_e32 v16, vcc, s0, v0
	s_mov_b32 s0, 0xb243000
	s_nop 0
	v_addc_co_u32_e32 v17, vcc, 0, v1, vcc
	v_add_co_u32_e32 v18, vcc, s0, v0
	s_mov_b32 s0, 0xb245000
	s_nop 0
	v_addc_co_u32_e32 v19, vcc, 0, v1, vcc
	v_add_co_u32_e32 v20, vcc, s0, v0
	s_mov_b32 s0, 0xb246000
	s_nop 0
	v_addc_co_u32_e32 v21, vcc, 0, v1, vcc
	v_add_co_u32_e32 v22, vcc, s0, v0
	s_mov_b32 s0, 0xb247000
	s_nop 0
	v_addc_co_u32_e32 v23, vcc, 0, v1, vcc
	v_add_co_u32_e32 v0, vcc, s0, v0
	v_readlane_b32 s0, v255, 7
	s_nop 0
	v_addc_co_u32_e32 v1, vcc, 0, v1, vcc
	v_readlane_b32 s1, v255, 8
	s_lshl_b64 s[0:1], s[0:1], 2
	s_add_u32 s0, s8, s0
	s_addc_u32 s1, s9, s1
	s_waitcnt vmcnt(0)
	v_lshl_or_b32 v6, v6, 16, v5
	v_lshl_or_b32 v7, v8, 16, v7
	v_lshl_or_b32 v8, v26, 16, v9
	v_lshl_or_b32 v9, v24, 16, v27
	global_store_dwordx4 v[2:3], v[6:9], off offset:96
	global_load_ushort v5, v[10:11], off offset:1792
	s_nop 0
	global_load_ushort v6, v[12:13], off offset:2304
	global_load_ushort v7, v[14:15], off offset:2816
	global_load_ushort v10, v[16:17], off offset:3328
	global_load_ushort v11, v[18:19], off offset:3840
	s_nop 0
	global_load_ushort v12, v[20:21], off offset:256
	global_load_ushort v13, v[22:23], off offset:768
	global_load_ushort v14, v[0:1], off offset:1280
	v_mov_b32_e32 v0, 0x500
	v_lshl_add_u32 v54, v4, 3, v0
	v_mov_b32_e32 v15, v236
	v_mov_b64_e32 v[0:1], s[10:11]
	v_mad_u64_u32 v[8:9], s[4:5], v54, s6, v[0:1]
	s_waitcnt vmcnt(0)
	v_lshl_or_b32 v4, v6, 16, v5
	v_lshl_or_b32 v5, v10, 16, v7
	v_lshl_or_b32 v6, v12, 16, v11
	v_lshl_or_b32 v7, v14, 16, v13
	global_store_dwordx4 v[2:3], v[4:7], off offset:112
	s_nop 0
	v_and_b32_e32 v14, 15, v15
	v_bfe_u32 v17, v15, 4, 2
	v_lshlrev_b32_e32 v19, 2, v14
	v_lshlrev_b32_e32 v2, 6, v17
	v_or_b32_e32 v21, 8, v17
	v_lshlrev_b32_e32 v160, 4, v14
	v_or_b32_e32 v23, 0x100, v19
	v_min_u32_e32 v3, 9, v21
	v_or_b32_e32 v20, v2, v19
	v_lshl_add_u64 v[0:1], s[0:1], 0, v[160:161]
	v_or_b32_e32 v16, v2, v23
	v_lshlrev_b32_e32 v24, 6, v3
	s_mov_b64 s[0:1], 0x2000
	v_lshlrev_b32_e32 v160, 1, v20
	v_lshl_add_u64 v[4:5], v[0:1], 0, s[0:1]
	v_add_co_u32_e32 v0, vcc, s20, v0
	v_lshl_add_u64 v[10:11], v[8:9], 0, v[160:161]
	v_lshlrev_b32_e32 v160, 1, v16
	v_or_b32_e32 v22, v24, v19
	v_addc_co_u32_e32 v1, vcc, 0, v1, vcc
	v_lshl_add_u64 v[12:13], v[8:9], 0, v[160:161]
	v_lshlrev_b32_e32 v160, 1, v22
	global_load_dwordx4 v[0:3], v[0:1], off
	s_nop 0
	global_load_dwordx4 v[4:7], v[4:5], off offset:1024
	v_lshl_add_u64 v[8:9], v[8:9], 0, v[160:161]
	global_load_dwordx2 v[42:43], v[10:11], off offset:512
	global_load_dwordx2 v[40:41], v[12:13], off offset:512
	global_load_dwordx2 v[34:35], v[8:9], off offset:512
	v_and_b32_e32 v8, 63, v15
	v_and_b32_e32 v9, 4, v15
	v_lshlrev_b32_e32 v160, 3, v8
	v_cmp_eq_u32_e64 s[36:37], 0, v9
	v_cmp_gt_u32_e64 s[38:39], 8, v14
	v_and_b32_e32 v14, 12, v19
	v_lshl_add_u64 v[8:9], s[8:9], 0, v[160:161]
	s_mov_b64 s[0:1], 0x16f00000
	v_lshl_add_u64 v[12:13], v[8:9], 0, s[0:1]
	v_cvt_f32_ubyte0_e32 v8, v14
	v_mul_f32_e32 v8, 0xbf549a78, v8
	v_exp_f32_e32 v56, v8
	v_or_b32_e32 v8, 1, v14
	v_cvt_f32_ubyte0_e32 v8, v8
	v_mul_f32_e32 v8, 0xbf549a78, v8
	v_exp_f32_e32 v57, v8
	v_or_b32_e32 v8, 2, v14
	v_cvt_f32_ubyte0_e32 v8, v8
	v_mul_f32_e32 v8, 0xbf549a78, v8
	v_exp_f32_e32 v58, v8
	v_or_b32_e32 v8, 3, v14
	v_cvt_f32_ubyte0_e32 v8, v8
	v_mul_f32_e32 v8, 0xbf549a78, v8
	v_exp_f32_e32 v59, v8
	v_mad_i64_i32 v[8:9], s[0:1], v54, s6, 0
	v_add_u32_e32 v18, 0x100, v16
	v_or_b32_e32 v24, v24, v23
	v_or_b32_e32 v8, v8, v160
	v_cmp_gt_u32_e32 vcc, 10, v21
	v_lshlrev_b32_e64 v55, v17, 1
	v_lshl_add_u64 v[10:11], s[10:11], 0, v[160:161]
	v_lshl_add_u64 v[14:15], s[10:11], 0, v[8:9]
	v_lshlrev_b32_e32 v8, 1, v16
	v_lshlrev_b32_e32 v16, 1, v18
	v_lshlrev_b32_e32 v18, 1, v24
	v_lshlrev_b32_e32 v20, 1, v20
	v_lshlrev_b32_e32 v22, 1, v22
	v_mov_b32_e32 v21, 0
	s_waitcnt vmcnt(0)
	s_branch .LBB0_508
.LBB0_507:
	s_or_b64 exec, exec, s[0:1]
	v_sub_u32_e32 v9, v17, v60
	v_cvt_f32_i32_e32 v9, v9
	v_lshlrev_b32_e32 v34, 16, v32
	v_and_b32_e32 v35, 0xffff0000, v32
	s_add_i32 s14, s14, 1
	v_rcp_iflag_f32_e32 v30, v9
	v_lshl_add_u64 v[14:15], v[14:15], 0, s[34:35]
	s_cmp_eq_u32 s14, 8
	v_mov_b32_e32 v21, v17
	v_pk_fma_f32 v[34:35], v[30:31], v[36:37], v[34:35] op_sel_hi:[0,1,1] neg_lo:[0,0,1] neg_hi:[0,0,1]
	v_cvt_pk_bf16_f32 v32, v34, v35
	v_lshlrev_b32_e32 v34, 16, v33
	v_and_b32_e32 v35, 0xffff0000, v33
	v_pk_fma_f32 v[30:31], v[30:31], v[38:39], v[34:35] op_sel_hi:[0,1,1] neg_lo:[0,0,1] neg_hi:[0,0,1]
	v_cvt_pk_bf16_f32 v33, v30, v31
	v_lshlrev_b64 v[30:31], 11, v[160:161]
	v_lshl_add_u64 v[30:31], v[12:13], 0, v[30:31]
	v_mov_b32_e32 v42, v24
	v_mov_b32_e32 v43, v25
	v_mov_b32_e32 v40, v26
	v_mov_b32_e32 v41, v27
	v_mov_b32_e32 v34, v28
	v_mov_b32_e32 v35, v29
	global_store_dwordx2 v[30:31], v[32:33], off
	s_cbranch_scc1 .LBB0_530
.LBB0_508:
	v_readlane_b32 s0, v255, 11
	v_readlane_b32 s1, v255, 12
	v_add_u32_e32 v160, s14, v54
	s_cmp_gt_u32 s14, 6
	v_mov_b64_e32 v[24:25], s[0:1]
	s_movk_i32 s0, 0x1200
	v_mad_u64_u32 v[30:31], s[0:1], v160, s0, v[24:25]
	v_mov_b32_e32 v24, v42
	v_mov_b32_e32 v25, v43
	v_mov_b32_e32 v26, v40
	v_mov_b32_e32 v27, v41
	v_mov_b32_e32 v28, v34
	v_mov_b32_e32 v29, v35
	s_cbranch_scc1 .LBB0_510
	v_lshl_add_u64 v[24:25], v[30:31], 0, s[34:35]
	v_mov_b32_e32 v9, v161
	v_mov_b32_e32 v17, v161
	v_lshl_add_u64 v[26:27], v[24:25], 0, v[8:9]
	v_lshl_add_u64 v[28:29], v[24:25], 0, v[16:17]
	v_mov_b32_e32 v19, v161
	v_lshl_add_u64 v[32:33], v[24:25], 0, v[18:19]
	global_load_dwordx2 v[24:25], v[26:27], off
	s_nop 0
	global_load_dwordx2 v[26:27], v[28:29], off
	s_nop 0
	global_load_dwordx2 v[28:29], v[32:33], off

.LBB0_526:
	s_or_b64 exec, exec, s[8:9]
.LBB0_527:
	s_or_b64 exec, exec, s[6:7]
	s_waitcnt vmcnt(0)
.LBB0_528:
	s_or_b64 exec, exec, s[4:5]
	v_lshrrev_b32_e32 v9, 6, v9
	v_and_b32_e32 v19, 63, v160
	v_cndmask_b32_e64 v9, v19, v9, s[38:39]
	v_cvt_f32_ubyte0_e32 v9, v9
	v_mul_f32_e32 v19, v56, v9
	v_mul_f32_e32 v19, 0.15915494, v19
	v_cos_f32_e32 v48, v19
	v_sin_f32_e32 v49, v19
	v_mul_f32_e32 v19, v57, v9
	v_mul_f32_e32 v19, 0.15915494, v19
	v_lshlrev_b32_e32 v51, 16, v43
	v_lshlrev_b32_e32 v50, 16, v42
	v_and_b32_e32 v43, 0xffff0000, v43
	v_and_b32_e32 v42, 0xffff0000, v42
	v_cos_f32_e32 v46, v19
	v_sin_f32_e32 v47, v19
	v_mul_f32_e32 v19, v58, v9
	v_mul_f32_e32 v9, v59, v9
	v_pk_mul_f32 v[52:53], v[42:43], v[42:43]
	v_mul_f32_e32 v19, 0.15915494, v19
	v_mul_f32_e32 v9, 0.15915494, v9
	v_pk_fma_f32 v[52:53], v[50:51], v[50:51], v[52:53]
	v_cos_f32_e32 v44, v19
	v_sin_f32_e32 v45, v19
	v_cos_f32_e32 v19, v9
	v_sin_f32_e32 v23, v9
	v_add_f32_e32 v9, v52, v53
	v_mov_b32_e32 v53, v1
	s_nop 0
	v_add_f32_dpp v9, v9, v9 quad_perm:[1,0,3,2] row_mask:0xf bank_mask:0xf bound_ctrl:1
	s_nop 1
	v_add_f32_dpp v9, v9, v9 quad_perm:[2,3,0,1] row_mask:0xf bank_mask:0xf bound_ctrl:1
	s_nop 1
	v_add_f32_dpp v9, v9, v9 row_ror:4 row_mask:0xf bank_mask:0xf bound_ctrl:1
	s_nop 1
	v_add_f32_dpp v9, v9, v9 row_ror:8 row_mask:0xf bank_mask:0xf bound_ctrl:1
	v_fmamk_f32 v9, v9, 0x3c800000, v237
	v_rsq_f32_e32 v21, v9
	s_nop 0
	v_mul_f32_e32 v9, v21, v50
	v_mul_f32_e32 v9, v0, v9
	ds_swizzle_b32 v50, v9 offset:swizzle(SWAP,4)
	v_mul_f32_e32 v205, v21, v42
	s_waitcnt lgkmcnt(0)
	v_mul_f32_e32 v50, v49, v50
	v_cndmask_b32_e64 v50, v50, -v50, s[36:37]
	v_fmac_f32_e32 v50, v48, v9
	v_cndmask_b32_e64 v52, v50, v9, s[40:41]
	v_pk_mul_f32 v[52:53], v[52:53], v[204:205]
	ds_swizzle_b32 v9, v53 offset:swizzle(SWAP,4)
	v_mul_f32_e32 v205, v21, v51
	v_cndmask_b32_e64 v42, v52, v52, s[40:41]
	v_cndmask_b32_e64 v42, v42, v42, s[40:41]
	v_cndmask_b32_e64 v42, v42, v42, s[40:41]
	s_waitcnt lgkmcnt(0)
	v_mul_f32_e32 v9, v47, v9
	v_cndmask_b32_e64 v9, v9, -v9, s[36:37]
	v_fmac_f32_e32 v9, v46, v53
	v_cndmask_b32_e64 v9, v9, v53, s[40:41]
	v_pk_mov_b32 v[50:51], v[8:9], v[2:3] op_sel:[1,0]
	s_nop 0
	v_pk_mul_f32 v[50:51], v[50:51], v[204:205]
	ds_swizzle_b32 v52, v51 offset:swizzle(SWAP,4)
	v_mov_b32_e32 v9, v50
	v_cndmask_b32_e64 v9, v9, v50, s[40:41]
	v_mul_f32_e32 v205, v21, v43
	s_waitcnt lgkmcnt(0)
	v_mul_f32_e32 v52, v45, v52
	v_cndmask_b32_e64 v52, v52, -v52, s[36:37]
	v_fmac_f32_e32 v52, v44, v51
	v_cndmask_b32_e64 v50, v52, v51, s[40:41]
	v_mov_b32_e32 v51, v3
	v_pk_mul_f32 v[50:51], v[50:51], v[204:205]
	ds_swizzle_b32 v21, v51 offset:swizzle(SWAP,4)
	v_cndmask_b32_e64 v43, v50, v50, s[40:41]
	v_cndmask_b32_e64 v50, v9, v9, s[40:41]
	v_cvt_pk_bf16_f32 v42, v42, v50
	s_waitcnt lgkmcnt(0)
	v_mul_f32_e32 v21, v23, v21
	v_cndmask_b32_e64 v21, v21, -v21, s[36:37]
	v_fmac_f32_e32 v21, v19, v51
	v_cndmask_b32_e64 v9, v21, v51, s[40:41]
	v_mul_f32_e32 v9, 0x3e38aa3b, v9
	v_mov_b32_e32 v21, v161
	v_cvt_pk_bf16_f32 v43, v43, v9
	v_lshl_add_u64 v[50:51], v[30:31], 0, v[20:21]
	global_store_dwordx2 v[50:51], v[42:43], off offset:512
	v_lshlrev_b32_e32 v43, 16, v41
	v_lshlrev_b32_e32 v42, 16, v40
	v_and_b32_e32 v41, 0xffff0000, v41
	v_and_b32_e32 v40, 0xffff0000, v40
	v_pk_mul_f32 v[50:51], v[40:41], v[40:41]
	s_nop 0
	v_pk_fma_f32 v[50:51], v[42:43], v[42:43], v[50:51]
	s_nop 0
	v_add_f32_e32 v9, v50, v51
	v_mov_b32_e32 v51, v1
	s_nop 0
	v_add_f32_dpp v9, v9, v9 quad_perm:[1,0,3,2] row_mask:0xf bank_mask:0xf bound_ctrl:1
	s_nop 1
	v_add_f32_dpp v9, v9, v9 quad_perm:[2,3,0,1] row_mask:0xf bank_mask:0xf bound_ctrl:1
	s_nop 1
	v_add_f32_dpp v9, v9, v9 row_ror:4 row_mask:0xf bank_mask:0xf bound_ctrl:1
	s_nop 1
	v_add_f32_dpp v9, v9, v9 row_ror:8 row_mask:0xf bank_mask:0xf bound_ctrl:1
	v_fmamk_f32 v9, v9, 0x3c800000, v237
	v_rsq_f32_e32 v21, v9
	s_nop 0
	v_mul_f32_e32 v9, v21, v42
	v_mul_f32_e32 v9, v0, v9
	ds_swizzle_b32 v42, v9 offset:swizzle(SWAP,4)
	v_mul_f32_e32 v205, v21, v40
	s_waitcnt lgkmcnt(0)
	v_mul_f32_e32 v42, v49, v42
	v_cndmask_b32_e64 v42, v42, -v42, s[36:37]
	v_fmac_f32_e32 v42, v48, v9
	v_cndmask_b32_e64 v50, v42, v9, s[40:41]
	v_pk_mul_f32 v[50:51], v[50:51], v[204:205]
	ds_swizzle_b32 v9, v51 offset:swizzle(SWAP,4)
	v_mul_f32_e32 v205, v21, v43
	v_cndmask_b32_e64 v40, v50, v50, s[40:41]
	v_cndmask_b32_e64 v40, v40, v40, s[40:41]
	v_cndmask_b32_e64 v40, v40, v40, s[40:41]
	s_waitcnt lgkmcnt(0)
	v_mul_f32_e32 v9, v47, v9
	v_cndmask_b32_e64 v9, v9, -v9, s[36:37]
	v_fmac_f32_e32 v9, v46, v51
	v_cndmask_b32_e64 v9, v9, v51, s[40:41]
	v_pk_mov_b32 v[42:43], v[8:9], v[2:3] op_sel:[1,0]
	s_nop 0
	v_pk_mul_f32 v[42:43], v[42:43], v[204:205]
	ds_swizzle_b32 v50, v43 offset:swizzle(SWAP,4)
	v_mov_b32_e32 v9, v42
	v_cndmask_b32_e64 v9, v9, v42, s[40:41]
	v_mul_f32_e32 v205, v21, v41
	v_cndmask_b32_e64 v9, v9, v9, s[40:41]
	s_waitcnt lgkmcnt(0)
	v_mul_f32_e32 v50, v45, v50
	v_cndmask_b32_e64 v50, v50, -v50, s[36:37]
	v_fmac_f32_e32 v50, v44, v43
	v_cndmask_b32_e64 v42, v50, v43, s[40:41]
	v_mov_b32_e32 v43, v3
	v_pk_mul_f32 v[42:43], v[42:43], v[204:205]
	ds_swizzle_b32 v21, v43 offset:swizzle(SWAP,4)
	v_cndmask_b32_e64 v41, v42, v42, s[40:41]
	v_cvt_pk_bf16_f32 v40, v40, v9
	v_mov_b32_e32 v9, v161
	s_waitcnt lgkmcnt(0)
	v_mul_f32_e32 v21, v23, v21
	v_cndmask_b32_e64 v21, v21, -v21, s[36:37]
	v_fmac_f32_e32 v21, v19, v43
	v_cndmask_b32_e64 v21, v21, v43, s[40:41]
	v_mul_f32_e32 v21, 0x3e38aa3b, v21
	v_cvt_pk_bf16_f32 v41, v41, v21
	v_lshl_add_u64 v[42:43], v[30:31], 0, v[8:9]
	global_store_dwordx2 v[42:43], v[40:41], off offset:512
	v_and_b32_e32 v43, 0xffff0000, v35
	v_and_b32_e32 v42, 0xffff0000, v34
	v_lshlrev_b32_e32 v41, 16, v35
	v_lshlrev_b32_e32 v40, 16, v34
	v_pk_mul_f32 v[34:35], v[42:43], v[42:43]
	s_nop 0
	v_pk_fma_f32 v[34:35], v[40:41], v[40:41], v[34:35]
	s_nop 0
	v_add_f32_e32 v9, v34, v35
	s_nop 1
	v_add_f32_dpp v9, v9, v9 quad_perm:[1,0,3,2] row_mask:0xf bank_mask:0xf bound_ctrl:1
	s_nop 1
	v_add_f32_dpp v9, v9, v9 quad_perm:[2,3,0,1] row_mask:0xf bank_mask:0xf bound_ctrl:1
	s_nop 1
	v_add_f32_dpp v9, v9, v9 row_ror:4 row_mask:0xf bank_mask:0xf bound_ctrl:1
	s_nop 1
	v_add_f32_dpp v9, v9, v9 row_ror:8 row_mask:0xf bank_mask:0xf bound_ctrl:1
	v_fmamk_f32 v9, v9, 0x3c800000, v237
	v_rsq_f32_e32 v9, v9
	s_nop 0
	v_mul_f32_e32 v21, v9, v40
	v_mul_f32_e32 v21, v4, v21
	ds_swizzle_b32 v34, v21 offset:swizzle(SWAP,4)
	s_waitcnt lgkmcnt(0)
	v_mul_f32_e32 v34, v49, v34
	v_cndmask_b32_e64 v34, v34, -v34, s[36:37]
	v_fmac_f32_e32 v34, v48, v21
	v_cndmask_b32_e64 v21, v34, v21, s[40:41]
	v_mul_f32_e32 v34, v9, v42
	v_mul_f32_e32 v34, v5, v34
	ds_swizzle_b32 v35, v34 offset:swizzle(SWAP,4)
	s_waitcnt lgkmcnt(0)
	v_mul_f32_e32 v35, v47, v35
	v_cndmask_b32_e64 v35, v35, -v35, s[36:37]
	v_fmac_f32_e32 v35, v46, v34
	v_cndmask_b32_e64 v34, v35, v34, s[40:41]
	v_mul_f32_e32 v35, v9, v41
	v_mul_f32_e32 v35, v6, v35
	ds_swizzle_b32 v40, v35 offset:swizzle(SWAP,4)
	v_mul_f32_e32 v9, v9, v43
	v_mul_f32_e32 v9, v7, v9
	s_waitcnt lgkmcnt(0)
	v_mul_f32_e32 v40, v45, v40
	v_cndmask_b32_e64 v40, v40, -v40, s[36:37]
	v_fmac_f32_e32 v40, v44, v35
	v_cndmask_b32_e64 v35, v40, v35, s[40:41]
	ds_swizzle_b32 v40, v9 offset:swizzle(SWAP,4)
	s_waitcnt lgkmcnt(0)
	v_mul_f32_e32 v23, v23, v40
	v_cndmask_b32_e64 v23, v23, -v23, s[36:37]
	v_fmac_f32_e32 v23, v19, v9
	v_cndmask_b32_e64 v9, v23, v9, s[40:41]
	s_and_saveexec_b64 s[0:1], vcc
	s_cbranch_execz .LBB0_507
	v_mov_b32_e32 v23, v161
	v_cvt_pk_bf16_f32 v34, v21, v34
	v_cvt_pk_bf16_f32 v35, v35, v9
	v_lshl_add_u64 v[30:31], v[30:31], 0, v[22:23]
	global_store_dwordx2 v[30:31], v[34:35], off offset:512
	s_branch .LBB0_507

.LBB0_531:
	s_andn2_saveexec_b64 s[2:3], s[42:43]
	s_cbranch_execz .LBB0_556
	v_readlane_b32 s0, v255, 7
	v_mov_b32_e32 v9, v236
	v_readlane_b32 s1, v255, 8
	s_lshl_b64 s[0:1], s[0:1], 2
	v_bfe_u32 v19, v9, 4, 2
	v_readlane_b32 s4, v254, 28
	v_and_b32_e32 v17, 15, v9
	v_or_b32_e32 v23, 8, v19
	v_readlane_b32 s5, v254, 29
	s_add_u32 s0, s4, s0
	v_min_u32_e32 v0, 9, v23
	s_addc_u32 s1, s5, s1
	v_lshlrev_b32_e32 v160, 4, v17
	v_readlane_b32 s6, v255, 11
	v_lshlrev_b32_e32 v21, 2, v17
	v_lshlrev_b32_e32 v12, 6, v19
	v_lshlrev_b32_e32 v24, 6, v0
	v_lshl_add_u64 v[0:1], s[0:1], 0, v[160:161]
	s_mov_b64 s[0:1], 0x2000
	v_readlane_b32 s7, v255, 12
	v_lshl_add_u32 v56, v81, 2, v81
	v_or_b32_e32 v18, 0x100, v21
	v_lshl_add_u64 v[4:5], v[0:1], 0, s[0:1]
	v_mov_b64_e32 v[10:11], s[6:7]
	s_movk_i32 s0, 0x1200
	v_or_b32_e32 v20, v12, v21
	v_or_b32_e32 v8, v12, v18
	v_mad_i64_i32 v[10:11], s[0:1], v56, s0, v[10:11]
	v_lshlrev_b32_e32 v160, 1, v20
	v_add_co_u32_e32 v0, vcc, s20, v0
	v_lshl_add_u64 v[12:13], v[10:11], 0, v[160:161]
	v_lshlrev_b32_e32 v160, 1, v8
	v_or_b32_e32 v22, v24, v21
	v_addc_co_u32_e32 v1, vcc, 0, v1, vcc
	v_lshl_add_u64 v[14:15], v[10:11], 0, v[160:161]
	v_lshlrev_b32_e32 v160, 1, v22
	global_load_dwordx4 v[0:3], v[0:1], off
	s_nop 0
	global_load_dwordx4 v[4:7], v[4:5], off offset:1024
	v_lshl_add_u64 v[10:11], v[10:11], 0, v[160:161]
	global_load_dwordx2 v[44:45], v[12:13], off offset:512
	global_load_dwordx2 v[42:43], v[14:15], off offset:512
	global_load_dwordx2 v[36:37], v[10:11], off offset:512
	v_and_b32_e32 v10, 63, v9
	v_and_b32_e32 v9, 4, v9
	v_cmp_eq_u32_e64 s[36:37], 0, v9
	v_and_b32_e32 v9, 12, v21
	v_cmp_gt_u32_e64 s[38:39], 8, v17
	v_cvt_f32_ubyte0_e32 v17, v9
	v_mul_f32_e32 v17, 0xbf549a78, v17
	v_exp_f32_e32 v58, v17
	v_or_b32_e32 v17, 1, v9
	v_cvt_f32_ubyte0_e32 v17, v17
	v_mul_f32_e32 v17, 0xbf549a78, v17
	v_exp_f32_e32 v59, v17
	v_or_b32_e32 v17, 2, v9
	v_or_b32_e32 v9, 3, v9
	v_cvt_f32_ubyte0_e32 v17, v17
	v_cvt_f32_ubyte0_e32 v9, v9
	v_mul_f32_e32 v17, 0xbf549a78, v17
	v_mul_f32_e32 v9, 0xbf549a78, v9
	v_exp_f32_e32 v60, v17
	v_exp_f32_e32 v61, v9
	v_lshlrev_b32_e32 v160, 3, v10
	v_add_u32_e32 v16, 0x100, v8
	v_or_b32_e32 v18, v24, v18
	v_mov_b32_e32 v63, 0
	v_lshl_add_u64 v[12:13], s[4:5], 0, v[160:161]
	s_mov_b64 s[0:1], 0x16f00000
	v_cmp_gt_u32_e32 vcc, 10, v23
	v_lshlrev_b32_e64 v57, v19, 1
	v_lshl_add_u64 v[10:11], s[6:7], 0, v[160:161]
	v_lshl_add_u64 v[14:15], v[12:13], 0, s[0:1]
	s_mov_b32 s14, 0
	v_lshlrev_b32_e32 v8, 1, v8
	v_lshlrev_b32_e32 v16, 1, v16
	v_lshlrev_b32_e32 v18, 1, v18
	v_lshlrev_b32_e32 v20, 1, v20
	v_lshlrev_b32_e32 v22, 1, v22
	v_mov_b32_e32 v62, v56
	v_mov_b32_e32 v21, 0
	v_mov_b32_e32 v38, 0
	v_mov_b32_e32 v39, v63
	v_mov_b32_e32 v40, 0
	v_mov_b32_e32 v41, v63
	s_waitcnt vmcnt(0)
	s_branch .LBB0_534
.LBB0_533:
	s_or_b64 exec, exec, s[0:1]
	v_sub_u32_e32 v9, v17, v63
	v_cvt_f32_i32_e32 v9, v9
	v_lshlrev_b32_e32 v36, 16, v34
	v_and_b32_e32 v37, 0xffff0000, v34
	s_add_i32 s14, s14, 1
	v_rcp_iflag_f32_e32 v32, v9
	v_lshlrev_b64 v[24:25], 11, v[24:25]
	v_lshl_add_u64 v[24:25], v[14:15], 0, v[24:25]
	v_add_u32_e32 v62, 1, v62
	v_pk_fma_f32 v[36:37], v[32:33], v[40:41], v[36:37] op_sel_hi:[0,1,1] neg_lo:[0,0,1] neg_hi:[0,0,1]
	v_cvt_pk_bf16_f32 v34, v36, v37
	v_lshlrev_b32_e32 v36, 16, v35
	v_and_b32_e32 v37, 0xffff0000, v35
	v_pk_fma_f32 v[32:33], v[32:33], v[38:39], v[36:37] op_sel_hi:[0,1,1] neg_lo:[0,0,1] neg_hi:[0,0,1]
	v_cvt_pk_bf16_f32 v35, v32, v33
	s_cmp_eq_u32 s14, 5
	v_mov_b32_e32 v21, v17
	v_mov_b32_e32 v44, v26
	v_mov_b32_e32 v45, v27
	v_mov_b32_e32 v42, v28
	v_mov_b32_e32 v43, v29
	v_mov_b32_e32 v36, v30
	v_mov_b32_e32 v37, v31
	global_store_dwordx2 v[24:25], v[34:35], off
	s_cbranch_scc1 .LBB0_556
.LBB0_534:
	v_readlane_b32 s0, v255, 11
	v_readlane_b32 s1, v255, 12
	v_add_u32_e32 v24, s14, v56
	s_cmp_gt_u32 s14, 3
	v_mov_b64_e32 v[26:27], s[0:1]
	s_movk_i32 s0, 0x1200
	v_mad_i64_i32 v[32:33], s[0:1], v24, s0, v[26:27]
	v_mov_b32_e32 v26, v44
	v_mov_b32_e32 v27, v45
	v_mov_b32_e32 v28, v42
	v_mov_b32_e32 v29, v43
	v_mov_b32_e32 v30, v36
	v_mov_b32_e32 v31, v37
	s_cbranch_scc1 .LBB0_536
	v_lshl_add_u64 v[26:27], v[32:33], 0, s[34:35]
	v_mov_b32_e32 v9, v161
	v_mov_b32_e32 v17, v161
	v_lshl_add_u64 v[28:29], v[26:27], 0, v[8:9]
	v_lshl_add_u64 v[30:31], v[26:27], 0, v[16:17]
	v_mov_b32_e32 v19, v161
	v_lshl_add_u64 v[34:35], v[26:27], 0, v[18:19]
	global_load_dwordx2 v[26:27], v[28:29], off
	s_nop 0
	global_load_dwordx2 v[28:29], v[30:31], off
	s_nop 0
	global_load_dwordx2 v[30:31], v[34:35], off

.LBB0_552:
	s_or_b64 exec, exec, s[8:9]
.LBB0_553:
	s_or_b64 exec, exec, s[6:7]
	s_waitcnt vmcnt(0)
.LBB0_554:
	s_or_b64 exec, exec, s[4:5]
	v_lshrrev_b32_e32 v9, 6, v9
	v_and_b32_e32 v19, 63, v24
	v_cndmask_b32_e64 v9, v19, v9, s[38:39]
	v_cvt_f32_ubyte0_e32 v9, v9
	v_mul_f32_e32 v19, v58, v9
	v_mul_f32_e32 v19, 0.15915494, v19
	v_cos_f32_e32 v50, v19
	v_sin_f32_e32 v51, v19
	v_mul_f32_e32 v19, v59, v9
	v_mul_f32_e32 v19, 0.15915494, v19
	v_lshlrev_b32_e32 v53, 16, v45
	v_lshlrev_b32_e32 v52, 16, v44
	v_and_b32_e32 v45, 0xffff0000, v45
	v_and_b32_e32 v44, 0xffff0000, v44
	v_cos_f32_e32 v48, v19
	v_sin_f32_e32 v49, v19
	v_mul_f32_e32 v19, v60, v9
	v_mul_f32_e32 v9, v61, v9
	v_pk_mul_f32 v[54:55], v[44:45], v[44:45]
	v_mul_f32_e32 v19, 0.15915494, v19
	v_mul_f32_e32 v9, 0.15915494, v9
	v_pk_fma_f32 v[54:55], v[52:53], v[52:53], v[54:55]
	v_cos_f32_e32 v46, v19
	v_sin_f32_e32 v47, v19
	v_cos_f32_e32 v19, v9
	v_sin_f32_e32 v23, v9
	v_add_f32_e32 v9, v54, v55
	v_mov_b32_e32 v55, v1
	s_nop 0
	v_add_f32_dpp v9, v9, v9 quad_perm:[1,0,3,2] row_mask:0xf bank_mask:0xf bound_ctrl:1
	s_nop 1
	v_add_f32_dpp v9, v9, v9 quad_perm:[2,3,0,1] row_mask:0xf bank_mask:0xf bound_ctrl:1
	s_nop 1
	v_add_f32_dpp v9, v9, v9 row_ror:4 row_mask:0xf bank_mask:0xf bound_ctrl:1
	s_nop 1
	v_add_f32_dpp v9, v9, v9 row_ror:8 row_mask:0xf bank_mask:0xf bound_ctrl:1
	v_fmamk_f32 v9, v9, 0x3c800000, v237
	v_rsq_f32_e32 v21, v9
	s_nop 0
	v_mul_f32_e32 v9, v21, v52
	v_mul_f32_e32 v9, v0, v9
	ds_swizzle_b32 v52, v9 offset:swizzle(SWAP,4)
	v_mul_f32_e32 v205, v21, v44
	s_waitcnt lgkmcnt(0)
	v_mul_f32_e32 v52, v51, v52
	v_cndmask_b32_e64 v52, v52, -v52, s[36:37]
	v_fmac_f32_e32 v52, v50, v9
	v_cndmask_b32_e64 v54, v52, v9, s[40:41]
	v_pk_mul_f32 v[54:55], v[54:55], v[204:205]
	ds_swizzle_b32 v9, v55 offset:swizzle(SWAP,4)
	v_mul_f32_e32 v205, v21, v53
	v_cndmask_b32_e64 v44, v54, v54, s[40:41]
	v_cndmask_b32_e64 v44, v44, v44, s[40:41]
	v_cndmask_b32_e64 v44, v44, v44, s[40:41]
	s_waitcnt lgkmcnt(0)
	v_mul_f32_e32 v9, v49, v9
	v_cndmask_b32_e64 v9, v9, -v9, s[36:37]
	v_fmac_f32_e32 v9, v48, v55
	v_cndmask_b32_e64 v9, v9, v55, s[40:41]
	v_pk_mov_b32 v[52:53], v[8:9], v[2:3] op_sel:[1,0]
	s_nop 0
	v_pk_mul_f32 v[52:53], v[52:53], v[204:205]
	ds_swizzle_b32 v54, v53 offset:swizzle(SWAP,4)
	v_mov_b32_e32 v9, v52
	v_cndmask_b32_e64 v9, v9, v52, s[40:41]
	v_mul_f32_e32 v205, v21, v45
	s_waitcnt lgkmcnt(0)
	v_mul_f32_e32 v54, v47, v54
	v_cndmask_b32_e64 v54, v54, -v54, s[36:37]
	v_fmac_f32_e32 v54, v46, v53
	v_cndmask_b32_e64 v52, v54, v53, s[40:41]
	v_mov_b32_e32 v53, v3
	v_pk_mul_f32 v[52:53], v[52:53], v[204:205]
	ds_swizzle_b32 v21, v53 offset:swizzle(SWAP,4)
	v_cndmask_b32_e64 v45, v52, v52, s[40:41]
	v_cndmask_b32_e64 v52, v9, v9, s[40:41]
	v_cvt_pk_bf16_f32 v44, v44, v52
	s_waitcnt lgkmcnt(0)
	v_mul_f32_e32 v21, v23, v21
	v_cndmask_b32_e64 v21, v21, -v21, s[36:37]
	v_fmac_f32_e32 v21, v19, v53
	v_cndmask_b32_e64 v9, v21, v53, s[40:41]
	v_mul_f32_e32 v9, 0x3e38aa3b, v9
	v_mov_b32_e32 v21, v161
	v_cvt_pk_bf16_f32 v45, v45, v9
	v_lshl_add_u64 v[52:53], v[32:33], 0, v[20:21]
	global_store_dwordx2 v[52:53], v[44:45], off offset:512
	v_lshlrev_b32_e32 v45, 16, v43
	v_lshlrev_b32_e32 v44, 16, v42
	v_and_b32_e32 v43, 0xffff0000, v43
	v_and_b32_e32 v42, 0xffff0000, v42
	v_pk_mul_f32 v[52:53], v[42:43], v[42:43]
	s_nop 0
	v_pk_fma_f32 v[52:53], v[44:45], v[44:45], v[52:53]
	s_nop 0
	v_add_f32_e32 v9, v52, v53
	v_mov_b32_e32 v53, v1
	s_nop 0
	v_add_f32_dpp v9, v9, v9 quad_perm:[1,0,3,2] row_mask:0xf bank_mask:0xf bound_ctrl:1
	s_nop 1
	v_add_f32_dpp v9, v9, v9 quad_perm:[2,3,0,1] row_mask:0xf bank_mask:0xf bound_ctrl:1
	s_nop 1
	v_add_f32_dpp v9, v9, v9 row_ror:4 row_mask:0xf bank_mask:0xf bound_ctrl:1
	s_nop 1
	v_add_f32_dpp v9, v9, v9 row_ror:8 row_mask:0xf bank_mask:0xf bound_ctrl:1
	v_fmamk_f32 v9, v9, 0x3c800000, v237
	v_rsq_f32_e32 v21, v9
	s_nop 0
	v_mul_f32_e32 v9, v21, v44
	v_mul_f32_e32 v9, v0, v9
	ds_swizzle_b32 v44, v9 offset:swizzle(SWAP,4)
	v_mul_f32_e32 v205, v21, v42
	s_waitcnt lgkmcnt(0)
	v_mul_f32_e32 v44, v51, v44
	v_cndmask_b32_e64 v44, v44, -v44, s[36:37]
	v_fmac_f32_e32 v44, v50, v9
	v_cndmask_b32_e64 v52, v44, v9, s[40:41]
	v_pk_mul_f32 v[52:53], v[52:53], v[204:205]
	ds_swizzle_b32 v9, v53 offset:swizzle(SWAP,4)
	v_mul_f32_e32 v205, v21, v45
	v_cndmask_b32_e64 v42, v52, v52, s[40:41]
	v_cndmask_b32_e64 v42, v42, v42, s[40:41]
	v_cndmask_b32_e64 v42, v42, v42, s[40:41]
	s_waitcnt lgkmcnt(0)
	v_mul_f32_e32 v9, v49, v9
	v_cndmask_b32_e64 v9, v9, -v9, s[36:37]
	v_fmac_f32_e32 v9, v48, v53
	v_cndmask_b32_e64 v9, v9, v53, s[40:41]
	v_pk_mov_b32 v[44:45], v[8:9], v[2:3] op_sel:[1,0]
	s_nop 0
	v_pk_mul_f32 v[44:45], v[44:45], v[204:205]
	ds_swizzle_b32 v52, v45 offset:swizzle(SWAP,4)
	v_mov_b32_e32 v9, v44
	v_cndmask_b32_e64 v9, v9, v44, s[40:41]
	v_mul_f32_e32 v205, v21, v43
	v_cndmask_b32_e64 v9, v9, v9, s[40:41]
	s_waitcnt lgkmcnt(0)
	v_mul_f32_e32 v52, v47, v52
	v_cndmask_b32_e64 v52, v52, -v52, s[36:37]
	v_fmac_f32_e32 v52, v46, v45
	v_cndmask_b32_e64 v44, v52, v45, s[40:41]
	v_mov_b32_e32 v45, v3
	v_pk_mul_f32 v[44:45], v[44:45], v[204:205]
	ds_swizzle_b32 v21, v45 offset:swizzle(SWAP,4)
	v_cndmask_b32_e64 v43, v44, v44, s[40:41]
	v_cvt_pk_bf16_f32 v42, v42, v9
	v_mov_b32_e32 v9, v161
	s_waitcnt lgkmcnt(0)
	v_mul_f32_e32 v21, v23, v21
	v_cndmask_b32_e64 v21, v21, -v21, s[36:37]
	v_fmac_f32_e32 v21, v19, v45
	v_cndmask_b32_e64 v21, v21, v45, s[40:41]
	v_mul_f32_e32 v21, 0x3e38aa3b, v21
	v_cvt_pk_bf16_f32 v43, v43, v21
	v_lshl_add_u64 v[44:45], v[32:33], 0, v[8:9]
	global_store_dwordx2 v[44:45], v[42:43], off offset:512
	v_and_b32_e32 v45, 0xffff0000, v37
	v_and_b32_e32 v44, 0xffff0000, v36
	v_lshlrev_b32_e32 v43, 16, v37
	v_lshlrev_b32_e32 v42, 16, v36
	v_pk_mul_f32 v[36:37], v[44:45], v[44:45]
	s_nop 0
	v_pk_fma_f32 v[36:37], v[42:43], v[42:43], v[36:37]
	s_nop 0
	v_add_f32_e32 v9, v36, v37
	s_nop 1
	v_add_f32_dpp v9, v9, v9 quad_perm:[1,0,3,2] row_mask:0xf bank_mask:0xf bound_ctrl:1
	s_nop 1
	v_add_f32_dpp v9, v9, v9 quad_perm:[2,3,0,1] row_mask:0xf bank_mask:0xf bound_ctrl:1
	s_nop 1
	v_add_f32_dpp v9, v9, v9 row_ror:4 row_mask:0xf bank_mask:0xf bound_ctrl:1
	s_nop 1
	v_add_f32_dpp v9, v9, v9 row_ror:8 row_mask:0xf bank_mask:0xf bound_ctrl:1
	v_fmamk_f32 v9, v9, 0x3c800000, v237
	v_rsq_f32_e32 v9, v9
	s_nop 0
	v_mul_f32_e32 v21, v9, v42
	v_mul_f32_e32 v21, v4, v21
	ds_swizzle_b32 v36, v21 offset:swizzle(SWAP,4)
	s_waitcnt lgkmcnt(0)
	v_mul_f32_e32 v36, v51, v36
	v_cndmask_b32_e64 v36, v36, -v36, s[36:37]
	v_fmac_f32_e32 v36, v50, v21
	v_cndmask_b32_e64 v21, v36, v21, s[40:41]
	v_mul_f32_e32 v36, v9, v44
	v_mul_f32_e32 v36, v5, v36
	ds_swizzle_b32 v37, v36 offset:swizzle(SWAP,4)
	s_waitcnt lgkmcnt(0)
	v_mul_f32_e32 v37, v49, v37
	v_cndmask_b32_e64 v37, v37, -v37, s[36:37]
	v_fmac_f32_e32 v37, v48, v36
	v_cndmask_b32_e64 v36, v37, v36, s[40:41]
	v_mul_f32_e32 v37, v9, v43
	v_mul_f32_e32 v37, v6, v37
	ds_swizzle_b32 v42, v37 offset:swizzle(SWAP,4)
	v_mul_f32_e32 v9, v9, v45
	v_mul_f32_e32 v9, v7, v9
	s_waitcnt lgkmcnt(0)
	v_mul_f32_e32 v42, v47, v42
	v_cndmask_b32_e64 v42, v42, -v42, s[36:37]
	v_fmac_f32_e32 v42, v46, v37
	v_cndmask_b32_e64 v37, v42, v37, s[40:41]
	ds_swizzle_b32 v42, v9 offset:swizzle(SWAP,4)
	s_waitcnt lgkmcnt(0)
	v_mul_f32_e32 v23, v23, v42
	v_cndmask_b32_e64 v23, v23, -v23, s[36:37]
	v_fmac_f32_e32 v23, v19, v9
	v_cndmask_b32_e64 v9, v23, v9, s[40:41]
	s_and_saveexec_b64 s[0:1], vcc
	s_cbranch_execz .LBB0_533
	v_mov_b32_e32 v23, v161
	v_cvt_pk_bf16_f32 v36, v21, v36
	v_cvt_pk_bf16_f32 v37, v37, v9
	v_lshl_add_u64 v[32:33], v[32:33], 0, v[22:23]
	global_store_dwordx2 v[32:33], v[36:37], off offset:512
	s_branch .LBB0_533
